# priority-toggle coalescing: removed 28 back-to-back s_setprio 0 / s_setprio 1 pairs in the 8-phase GEMM loops
# speedup vs baseline: 1.0028x; 1.0028x over previous
.LBB0_181:
	ds_read_b128 v[128:131], v173
	ds_read_b128 v[132:135], v173 offset:1024
	ds_read_b128 v[136:139], v173 offset:2048
	ds_read_b128 v[140:143], v173 offset:3072
	ds_read_b128 v[162:165], v174
	ds_read_b128 v[166:169], v174 offset:1024
	ds_read_b128 v[176:179], v174 offset:2048
	ds_read_b128 v[180:183], v174 offset:3072
	s_add_u32 s6, s4, 0xfff80080
	s_addc_u32 s7, s5, -1
	s_cmp_eq_u32 s96, 28
	s_cselect_b32 s9, s26, s7
	s_cselect_b32 s8, s27, s6
	s_cselect_b32 s7, s86, s95
	s_cselect_b32 s6, s91, s94
	v_lshl_add_u64 v[216:217], s[4:5], 0, v[158:159]
	s_add_i32 m0, s47, 0xc000
	ds_read_b128 v[184:187], v175
	ds_read_b128 v[188:191], v175 offset:1024
	ds_read_b128 v[192:195], v175 offset:2048
	ds_read_b128 v[196:199], v175 offset:3072
	ds_read_b128 v[200:203], v175 offset:4096
	ds_read_b128 v[204:207], v175 offset:5120
	ds_read_b128 v[208:211], v175 offset:6144
	ds_read_b128 v[212:215], v175 offset:7168
	global_load_lds_dwordx4 v[216:217], off
	v_lshl_add_u64 v[216:217], s[4:5], 0, v[160:161]
	s_add_i32 m0, s47, 0xe000
	s_nop 0
	global_load_lds_dwordx4 v[216:217], off
	s_waitcnt vmcnt(8)
	s_waitcnt lgkmcnt(0)
	s_barrier
	s_setprio 1
	s_waitcnt lgkmcnt(0)
	v_mfma_f32_16x16x32_bf16 v[124:127], v[128:131], v[184:187], v[124:127]
	v_mfma_f32_16x16x32_bf16 v[120:123], v[136:139], v[184:187], v[120:123]
	v_mfma_f32_16x16x32_bf16 v[108:111], v[128:131], v[192:195], v[108:111]
	v_mfma_f32_16x16x32_bf16 v[104:107], v[136:139], v[192:195], v[104:107]
	v_mfma_f32_16x16x32_bf16 v[92:95], v[128:131], v[200:203], v[92:95]
	v_mfma_f32_16x16x32_bf16 v[88:91], v[136:139], v[200:203], v[88:91]
	v_mfma_f32_16x16x32_bf16 v[76:79], v[128:131], v[208:211], v[76:79]
	v_mfma_f32_16x16x32_bf16 v[72:75], v[136:139], v[208:211], v[72:75]
	v_mfma_f32_16x16x32_bf16 v[124:127], v[132:135], v[188:191], v[124:127]
	v_mfma_f32_16x16x32_bf16 v[120:123], v[140:143], v[188:191], v[120:123]
	v_mfma_f32_16x16x32_bf16 v[108:111], v[132:135], v[196:199], v[108:111]
	v_mfma_f32_16x16x32_bf16 v[104:107], v[140:143], v[196:199], v[104:107]
	v_mfma_f32_16x16x32_bf16 v[92:95], v[132:135], v[204:207], v[92:95]
	v_mfma_f32_16x16x32_bf16 v[88:91], v[140:143], v[204:207], v[88:91]
	v_mfma_f32_16x16x32_bf16 v[76:79], v[132:135], v[212:215], v[76:79]
	v_mfma_f32_16x16x32_bf16 v[72:75], v[140:143], v[212:215], v[72:75]
	v_mfma_f32_16x16x32_bf16 v[116:119], v[162:165], v[184:187], v[116:119]
	v_mfma_f32_16x16x32_bf16 v[112:115], v[176:179], v[184:187], v[112:115]
	v_mfma_f32_16x16x32_bf16 v[100:103], v[162:165], v[192:195], v[100:103]
	v_mfma_f32_16x16x32_bf16 v[96:99], v[176:179], v[192:195], v[96:99]
	v_mfma_f32_16x16x32_bf16 v[84:87], v[162:165], v[200:203], v[84:87]
	v_mfma_f32_16x16x32_bf16 v[80:83], v[176:179], v[200:203], v[80:83]
	v_mfma_f32_16x16x32_bf16 v[68:71], v[162:165], v[208:211], v[68:71]
	v_mfma_f32_16x16x32_bf16 v[64:67], v[176:179], v[208:211], v[64:67]
	v_mfma_f32_16x16x32_bf16 v[116:119], v[166:169], v[188:191], v[116:119]
	v_mfma_f32_16x16x32_bf16 v[112:115], v[180:183], v[188:191], v[112:115]
	v_mfma_f32_16x16x32_bf16 v[100:103], v[166:169], v[196:199], v[100:103]
	v_mfma_f32_16x16x32_bf16 v[96:99], v[180:183], v[196:199], v[96:99]
	v_mfma_f32_16x16x32_bf16 v[84:87], v[166:169], v[204:207], v[84:87]
	v_mfma_f32_16x16x32_bf16 v[80:83], v[180:183], v[204:207], v[80:83]
	v_mfma_f32_16x16x32_bf16 v[68:71], v[166:169], v[212:215], v[68:71]
	v_mfma_f32_16x16x32_bf16 v[64:67], v[180:183], v[212:215], v[64:67]
	s_setprio 0
	s_barrier
	s_add_i32 s97, s30, s44
	v_lshl_add_u64 v[216:217], s[6:7], 0, v[146:147]
	s_mov_b32 m0, s97
	ds_read_b128 v[184:187], v175 offset:16384
	ds_read_b128 v[188:191], v175 offset:17408
	ds_read_b128 v[192:195], v175 offset:18432
	ds_read_b128 v[196:199], v175 offset:19456
	ds_read_b128 v[200:203], v175 offset:20480
	ds_read_b128 v[204:207], v175 offset:21504
	ds_read_b128 v[208:211], v175 offset:22528
	ds_read_b128 v[212:215], v175 offset:23552
	global_load_lds_dwordx4 v[216:217], off
	s_add_i32 m0, s97, 0x2000
	s_add_u32 vcc_lo, s6, 0x80000
	v_lshl_add_u64 v[218:219], s[6:7], 0, v[144:145]
	s_addc_u32 vcc_hi, s7, 0
	s_add_i32 s97, s31, s44
	global_load_lds_dwordx4 v[218:219], off
	v_lshl_add_u64 v[220:221], vcc, 0, v[146:147]
	s_mov_b32 m0, s97
	v_lshl_add_u64 v[222:223], s[8:9], 0, v[144:145]
	global_load_lds_dwordx4 v[220:221], off
	v_lshl_add_u64 v[220:221], vcc, 0, v[144:145]
	s_add_i32 m0, s97, 0x2000
	s_nop 0
	global_load_lds_dwordx4 v[220:221], off
	v_lshl_add_u64 v[220:221], s[8:9], 0, v[146:147]
	s_mov_b32 m0, s47
	s_nop 0
	global_load_lds_dwordx4 v[220:221], off
	s_mov_b32 m0, s48
	s_nop 0
	global_load_lds_dwordx4 v[222:223], off
	s_waitcnt vmcnt(8)
	s_waitcnt lgkmcnt(0)
	s_barrier
	s_setprio 1
	s_waitcnt lgkmcnt(0)
	v_mfma_f32_16x16x32_bf16 v[60:63], v[128:131], v[184:187], v[60:63]
	v_mfma_f32_16x16x32_bf16 v[56:59], v[136:139], v[184:187], v[56:59]
	v_mfma_f32_16x16x32_bf16 v[44:47], v[128:131], v[192:195], v[44:47]
	v_mfma_f32_16x16x32_bf16 v[40:43], v[136:139], v[192:195], v[40:43]
	v_mfma_f32_16x16x32_bf16 v[28:31], v[128:131], v[200:203], v[28:31]
	v_mfma_f32_16x16x32_bf16 v[24:27], v[136:139], v[200:203], v[24:27]
	v_mfma_f32_16x16x32_bf16 v[12:15], v[128:131], v[208:211], v[12:15]
	v_mfma_f32_16x16x32_bf16 v[8:11], v[136:139], v[208:211], v[8:11]
	v_mfma_f32_16x16x32_bf16 v[60:63], v[132:135], v[188:191], v[60:63]
	v_mfma_f32_16x16x32_bf16 v[56:59], v[140:143], v[188:191], v[56:59]
	v_mfma_f32_16x16x32_bf16 v[44:47], v[132:135], v[196:199], v[44:47]
	v_mfma_f32_16x16x32_bf16 v[40:43], v[140:143], v[196:199], v[40:43]
	v_mfma_f32_16x16x32_bf16 v[28:31], v[132:135], v[204:207], v[28:31]
	v_mfma_f32_16x16x32_bf16 v[24:27], v[140:143], v[204:207], v[24:27]
	v_mfma_f32_16x16x32_bf16 v[12:15], v[132:135], v[212:215], v[12:15]
	v_mfma_f32_16x16x32_bf16 v[8:11], v[140:143], v[212:215], v[8:11]
	v_mfma_f32_16x16x32_bf16 v[52:55], v[162:165], v[184:187], v[52:55]
	v_mfma_f32_16x16x32_bf16 v[48:51], v[176:179], v[184:187], v[48:51]
	v_mfma_f32_16x16x32_bf16 v[36:39], v[162:165], v[192:195], v[36:39]
	v_mfma_f32_16x16x32_bf16 v[32:35], v[176:179], v[192:195], v[32:35]
	v_mfma_f32_16x16x32_bf16 v[20:23], v[162:165], v[200:203], v[20:23]
	v_mfma_f32_16x16x32_bf16 v[16:19], v[176:179], v[200:203], v[16:19]
	v_mfma_f32_16x16x32_bf16 v[4:7], v[162:165], v[208:211], v[4:7]
	v_mfma_f32_16x16x32_bf16 v[0:3], v[176:179], v[208:211], v[0:3]
	v_mfma_f32_16x16x32_bf16 v[52:55], v[166:169], v[188:191], v[52:55]
	v_mfma_f32_16x16x32_bf16 v[48:51], v[180:183], v[188:191], v[48:51]
	v_mfma_f32_16x16x32_bf16 v[36:39], v[166:169], v[196:199], v[36:39]
	v_mfma_f32_16x16x32_bf16 v[32:35], v[180:183], v[196:199], v[32:35]
	v_mfma_f32_16x16x32_bf16 v[20:23], v[166:169], v[204:207], v[20:23]
	v_mfma_f32_16x16x32_bf16 v[16:19], v[180:183], v[204:207], v[16:19]
	v_mfma_f32_16x16x32_bf16 v[4:7], v[166:169], v[212:215], v[4:7]
	v_mfma_f32_16x16x32_bf16 v[0:3], v[180:183], v[212:215], v[0:3]
	s_setprio 0
	s_barrier
	s_add_i32 s97, 0, 0x18000
	s_add_i32 vcc_lo, 0, 0x1c000
	v_add_u32_e32 v140, s97, v153
	v_add_u32_e32 v180, vcc_lo, v153
	ds_read_b128 v[128:131], v140
	ds_read_b128 v[132:135], v140 offset:1024
	ds_read_b128 v[136:139], v140 offset:2048
	ds_read_b128 v[140:143], v140 offset:3072
	ds_read_b128 v[162:165], v180
	ds_read_b128 v[166:169], v180 offset:1024
	ds_read_b128 v[176:179], v180 offset:2048
	ds_read_b128 v[180:183], v180 offset:3072
	s_add_u32 s8, s8, 0x80000
	s_addc_u32 s9, s9, 0
	s_mov_b32 m0, s49
	v_lshl_add_u64 v[224:225], s[8:9], 0, v[146:147]
	ds_read_b128 v[184:187], v175 offset:32768
	ds_read_b128 v[188:191], v175 offset:33792
	ds_read_b128 v[192:195], v175 offset:34816
	ds_read_b128 v[196:199], v175 offset:35840
	ds_read_b128 v[200:203], v175 offset:36864
	ds_read_b128 v[204:207], v175 offset:37888
	ds_read_b128 v[208:211], v175 offset:38912
	ds_read_b128 v[212:215], v175 offset:39936
	global_load_lds_dwordx4 v[224:225], off
	v_lshl_add_u64 v[224:225], s[8:9], 0, v[144:145]
	s_mov_b32 m0, s50
	s_nop 0
	global_load_lds_dwordx4 v[224:225], off
	s_waitcnt vmcnt(8)
	s_waitcnt lgkmcnt(0)
	s_barrier
	s_setprio 1
	s_waitcnt lgkmcnt(0)
	v_mfma_f32_16x16x32_bf16 v[124:127], v[128:131], v[184:187], v[124:127]
	v_mfma_f32_16x16x32_bf16 v[120:123], v[136:139], v[184:187], v[120:123]
	v_mfma_f32_16x16x32_bf16 v[108:111], v[128:131], v[192:195], v[108:111]
	v_mfma_f32_16x16x32_bf16 v[104:107], v[136:139], v[192:195], v[104:107]
	v_mfma_f32_16x16x32_bf16 v[92:95], v[128:131], v[200:203], v[92:95]
	v_mfma_f32_16x16x32_bf16 v[88:91], v[136:139], v[200:203], v[88:91]
	v_mfma_f32_16x16x32_bf16 v[76:79], v[128:131], v[208:211], v[76:79]
	v_mfma_f32_16x16x32_bf16 v[72:75], v[136:139], v[208:211], v[72:75]
	v_mfma_f32_16x16x32_bf16 v[124:127], v[132:135], v[188:191], v[124:127]
	v_mfma_f32_16x16x32_bf16 v[120:123], v[140:143], v[188:191], v[120:123]
	v_mfma_f32_16x16x32_bf16 v[108:111], v[132:135], v[196:199], v[108:111]
	v_mfma_f32_16x16x32_bf16 v[104:107], v[140:143], v[196:199], v[104:107]
	v_mfma_f32_16x16x32_bf16 v[92:95], v[132:135], v[204:207], v[92:95]
	v_mfma_f32_16x16x32_bf16 v[88:91], v[140:143], v[204:207], v[88:91]
	v_mfma_f32_16x16x32_bf16 v[76:79], v[132:135], v[212:215], v[76:79]
	v_mfma_f32_16x16x32_bf16 v[72:75], v[140:143], v[212:215], v[72:75]
	v_mfma_f32_16x16x32_bf16 v[116:119], v[162:165], v[184:187], v[116:119]
	v_mfma_f32_16x16x32_bf16 v[112:115], v[176:179], v[184:187], v[112:115]
	v_mfma_f32_16x16x32_bf16 v[100:103], v[162:165], v[192:195], v[100:103]
	v_mfma_f32_16x16x32_bf16 v[96:99], v[176:179], v[192:195], v[96:99]
	v_mfma_f32_16x16x32_bf16 v[84:87], v[162:165], v[200:203], v[84:87]
	v_mfma_f32_16x16x32_bf16 v[80:83], v[176:179], v[200:203], v[80:83]
	v_mfma_f32_16x16x32_bf16 v[68:71], v[162:165], v[208:211], v[68:71]
	v_mfma_f32_16x16x32_bf16 v[64:67], v[176:179], v[208:211], v[64:67]
	v_mfma_f32_16x16x32_bf16 v[116:119], v[166:169], v[188:191], v[116:119]
	v_mfma_f32_16x16x32_bf16 v[112:115], v[180:183], v[188:191], v[112:115]
	v_mfma_f32_16x16x32_bf16 v[100:103], v[166:169], v[196:199], v[100:103]
	v_mfma_f32_16x16x32_bf16 v[96:99], v[180:183], v[196:199], v[96:99]
	v_mfma_f32_16x16x32_bf16 v[84:87], v[166:169], v[204:207], v[84:87]
	v_mfma_f32_16x16x32_bf16 v[80:83], v[180:183], v[204:207], v[80:83]
	v_mfma_f32_16x16x32_bf16 v[68:71], v[166:169], v[212:215], v[68:71]
	v_mfma_f32_16x16x32_bf16 v[64:67], v[180:183], v[212:215], v[64:67]
	s_setprio 0
	s_barrier
	s_add_i32 s8, s97, s44
	v_lshl_add_u64 v[216:217], v[216:217], 0, s[78:79]
	s_mov_b32 m0, s8
	ds_read_b128 v[184:187], v175 offset:49152
	ds_read_b128 v[188:191], v175 offset:50176
	ds_read_b128 v[192:195], v175 offset:51200
	ds_read_b128 v[196:199], v175 offset:52224
	ds_read_b128 v[200:203], v175 offset:53248
	ds_read_b128 v[204:207], v175 offset:54272
	ds_read_b128 v[208:211], v175 offset:55296
	ds_read_b128 v[212:215], v175 offset:56320
	global_load_lds_dwordx4 v[216:217], off
	s_add_i32 m0, s8, 0x2000
	s_add_u32 s6, s6, 0x80080
	v_lshl_add_u64 v[216:217], v[218:219], 0, s[78:79]
	s_addc_u32 s7, s7, 0
	s_add_i32 s8, vcc_lo, s44
	global_load_lds_dwordx4 v[216:217], off
	v_lshl_add_u64 v[216:217], s[6:7], 0, v[146:147]
	s_mov_b32 m0, s8
	s_nop 0
	global_load_lds_dwordx4 v[216:217], off
	v_lshl_add_u64 v[216:217], s[6:7], 0, v[144:145]
	s_add_i32 m0, s8, 0x2000
	s_nop 0
	global_load_lds_dwordx4 v[216:217], off
	v_lshl_add_u64 v[216:217], v[220:221], 0, s[78:79]
	s_mov_b32 m0, s71
	s_nop 0
	global_load_lds_dwordx4 v[216:217], off
	v_lshl_add_u64 v[216:217], v[222:223], 0, s[78:79]
	s_mov_b32 m0, s84
	s_nop 0
	global_load_lds_dwordx4 v[216:217], off
	s_waitcnt vmcnt(8)
	s_waitcnt lgkmcnt(0)
	s_barrier
	s_setprio 1
	s_waitcnt lgkmcnt(0)
	v_mfma_f32_16x16x32_bf16 v[60:63], v[128:131], v[184:187], v[60:63]
	v_mfma_f32_16x16x32_bf16 v[56:59], v[136:139], v[184:187], v[56:59]
	v_mfma_f32_16x16x32_bf16 v[44:47], v[128:131], v[192:195], v[44:47]
	v_mfma_f32_16x16x32_bf16 v[40:43], v[136:139], v[192:195], v[40:43]
	v_mfma_f32_16x16x32_bf16 v[28:31], v[128:131], v[200:203], v[28:31]
	v_mfma_f32_16x16x32_bf16 v[24:27], v[136:139], v[200:203], v[24:27]
	v_mfma_f32_16x16x32_bf16 v[12:15], v[128:131], v[208:211], v[12:15]
	v_mfma_f32_16x16x32_bf16 v[8:11], v[136:139], v[208:211], v[8:11]
	v_mfma_f32_16x16x32_bf16 v[60:63], v[132:135], v[188:191], v[60:63]
	v_mfma_f32_16x16x32_bf16 v[56:59], v[140:143], v[188:191], v[56:59]
	v_mfma_f32_16x16x32_bf16 v[44:47], v[132:135], v[196:199], v[44:47]
	v_mfma_f32_16x16x32_bf16 v[40:43], v[140:143], v[196:199], v[40:43]
	v_mfma_f32_16x16x32_bf16 v[28:31], v[132:135], v[204:207], v[28:31]
	v_mfma_f32_16x16x32_bf16 v[24:27], v[140:143], v[204:207], v[24:27]
	v_mfma_f32_16x16x32_bf16 v[12:15], v[132:135], v[212:215], v[12:15]
	v_mfma_f32_16x16x32_bf16 v[8:11], v[140:143], v[212:215], v[8:11]
	v_mfma_f32_16x16x32_bf16 v[52:55], v[162:165], v[184:187], v[52:55]
	v_mfma_f32_16x16x32_bf16 v[48:51], v[176:179], v[184:187], v[48:51]
	v_mfma_f32_16x16x32_bf16 v[36:39], v[162:165], v[192:195], v[36:39]
	v_mfma_f32_16x16x32_bf16 v[32:35], v[176:179], v[192:195], v[32:35]
	v_mfma_f32_16x16x32_bf16 v[20:23], v[162:165], v[200:203], v[20:23]
	v_mfma_f32_16x16x32_bf16 v[16:19], v[176:179], v[200:203], v[16:19]
	v_mfma_f32_16x16x32_bf16 v[4:7], v[162:165], v[208:211], v[4:7]
	v_mfma_f32_16x16x32_bf16 v[0:3], v[176:179], v[208:211], v[0:3]
	v_mfma_f32_16x16x32_bf16 v[52:55], v[166:169], v[188:191], v[52:55]
	v_mfma_f32_16x16x32_bf16 v[48:51], v[180:183], v[188:191], v[48:51]
	v_mfma_f32_16x16x32_bf16 v[36:39], v[166:169], v[196:199], v[36:39]
	v_mfma_f32_16x16x32_bf16 v[32:35], v[180:183], v[196:199], v[32:35]
	v_mfma_f32_16x16x32_bf16 v[20:23], v[166:169], v[204:207], v[20:23]
	v_mfma_f32_16x16x32_bf16 v[16:19], v[180:183], v[204:207], v[16:19]
	v_mfma_f32_16x16x32_bf16 v[4:7], v[166:169], v[212:215], v[4:7]
	v_mfma_f32_16x16x32_bf16 v[0:3], v[180:183], v[212:215], v[0:3]
	s_setprio 0
	s_barrier
	s_add_i32 s96, s96, 2
	s_add_u32 s4, s4, 0x100
	s_addc_u32 s5, s5, 0
	s_add_u32 s94, s94, 0x100
	s_addc_u32 s95, s95, 0
	s_cmp_gt_u32 s96, 29
	s_cbranch_scc0 .LBB0_181
	s_and_b64 vcc, exec, s[88:89]
	s_cbranch_vccz .LBB0_184
	s_barrier

.LBB0_468:
	ds_read_b128 v[128:131], v173
	ds_read_b128 v[132:135], v173 offset:1024
	ds_read_b128 v[136:139], v173 offset:2048
	ds_read_b128 v[140:143], v173 offset:3072
	ds_read_b128 v[162:165], v174
	ds_read_b128 v[166:169], v174 offset:1024
	ds_read_b128 v[176:179], v174 offset:2048
	ds_read_b128 v[180:183], v174 offset:3072
	s_add_u32 s6, s4, 0xfff80080
	s_addc_u32 s7, s5, -1
	s_cmp_eq_u32 s85, 28
	s_cselect_b32 s9, s26, s7
	s_cselect_b32 s8, s27, s6
	s_cselect_b32 s7, s35, s84
	s_cselect_b32 s6, s68, s77
	v_lshl_add_u64 v[216:217], s[4:5], 0, v[158:159]
	s_add_i32 m0, s44, 0xc000
	ds_read_b128 v[184:187], v175
	ds_read_b128 v[188:191], v175 offset:1024
	ds_read_b128 v[192:195], v175 offset:2048
	ds_read_b128 v[196:199], v175 offset:3072
	ds_read_b128 v[200:203], v175 offset:4096
	ds_read_b128 v[204:207], v175 offset:5120
	ds_read_b128 v[208:211], v175 offset:6144
	ds_read_b128 v[212:215], v175 offset:7168
	global_load_lds_dwordx4 v[216:217], off
	v_lshl_add_u64 v[216:217], s[4:5], 0, v[160:161]
	s_add_i32 m0, s44, 0xe000
	s_nop 0
	global_load_lds_dwordx4 v[216:217], off
	s_waitcnt vmcnt(8)
	s_waitcnt lgkmcnt(0)
	s_barrier
	s_setprio 1
	s_waitcnt lgkmcnt(0)
	v_mfma_f32_16x16x32_bf16 v[124:127], v[128:131], v[184:187], v[124:127]
	v_mfma_f32_16x16x32_bf16 v[120:123], v[136:139], v[184:187], v[120:123]
	v_mfma_f32_16x16x32_bf16 v[108:111], v[128:131], v[192:195], v[108:111]
	v_mfma_f32_16x16x32_bf16 v[104:107], v[136:139], v[192:195], v[104:107]
	v_mfma_f32_16x16x32_bf16 v[92:95], v[128:131], v[200:203], v[92:95]
	v_mfma_f32_16x16x32_bf16 v[88:91], v[136:139], v[200:203], v[88:91]
	v_mfma_f32_16x16x32_bf16 v[76:79], v[128:131], v[208:211], v[76:79]
	v_mfma_f32_16x16x32_bf16 v[72:75], v[136:139], v[208:211], v[72:75]
	v_mfma_f32_16x16x32_bf16 v[124:127], v[132:135], v[188:191], v[124:127]
	v_mfma_f32_16x16x32_bf16 v[120:123], v[140:143], v[188:191], v[120:123]
	v_mfma_f32_16x16x32_bf16 v[108:111], v[132:135], v[196:199], v[108:111]
	v_mfma_f32_16x16x32_bf16 v[104:107], v[140:143], v[196:199], v[104:107]
	v_mfma_f32_16x16x32_bf16 v[92:95], v[132:135], v[204:207], v[92:95]
	v_mfma_f32_16x16x32_bf16 v[88:91], v[140:143], v[204:207], v[88:91]
	v_mfma_f32_16x16x32_bf16 v[76:79], v[132:135], v[212:215], v[76:79]
	v_mfma_f32_16x16x32_bf16 v[72:75], v[140:143], v[212:215], v[72:75]
	v_mfma_f32_16x16x32_bf16 v[116:119], v[162:165], v[184:187], v[116:119]
	v_mfma_f32_16x16x32_bf16 v[112:115], v[176:179], v[184:187], v[112:115]
	v_mfma_f32_16x16x32_bf16 v[100:103], v[162:165], v[192:195], v[100:103]
	v_mfma_f32_16x16x32_bf16 v[96:99], v[176:179], v[192:195], v[96:99]
	v_mfma_f32_16x16x32_bf16 v[84:87], v[162:165], v[200:203], v[84:87]
	v_mfma_f32_16x16x32_bf16 v[80:83], v[176:179], v[200:203], v[80:83]
	v_mfma_f32_16x16x32_bf16 v[68:71], v[162:165], v[208:211], v[68:71]
	v_mfma_f32_16x16x32_bf16 v[64:67], v[176:179], v[208:211], v[64:67]
	v_mfma_f32_16x16x32_bf16 v[116:119], v[166:169], v[188:191], v[116:119]
	v_mfma_f32_16x16x32_bf16 v[112:115], v[180:183], v[188:191], v[112:115]
	v_mfma_f32_16x16x32_bf16 v[100:103], v[166:169], v[196:199], v[100:103]
	v_mfma_f32_16x16x32_bf16 v[96:99], v[180:183], v[196:199], v[96:99]
	v_mfma_f32_16x16x32_bf16 v[84:87], v[166:169], v[204:207], v[84:87]
	v_mfma_f32_16x16x32_bf16 v[80:83], v[180:183], v[204:207], v[80:83]
	v_mfma_f32_16x16x32_bf16 v[68:71], v[166:169], v[212:215], v[68:71]
	v_mfma_f32_16x16x32_bf16 v[64:67], v[180:183], v[212:215], v[64:67]
	s_setprio 0
	s_barrier
	s_add_i32 s89, s51, s43
	v_lshl_add_u64 v[216:217], s[6:7], 0, v[144:145]
	s_mov_b32 m0, s89
	ds_read_b128 v[184:187], v175 offset:16384
	ds_read_b128 v[188:191], v175 offset:17408
	ds_read_b128 v[192:195], v175 offset:18432
	ds_read_b128 v[196:199], v175 offset:19456
	ds_read_b128 v[200:203], v175 offset:20480
	ds_read_b128 v[204:207], v175 offset:21504
	ds_read_b128 v[208:211], v175 offset:22528
	ds_read_b128 v[212:215], v175 offset:23552
	global_load_lds_dwordx4 v[216:217], off
	s_add_i32 m0, s89, 0x2000
	s_add_u32 s90, s6, 0x80000
	v_lshl_add_u64 v[218:219], s[6:7], 0, v[146:147]
	s_addc_u32 s91, s7, 0
	s_add_i32 s89, s65, s43
	global_load_lds_dwordx4 v[218:219], off
	v_lshl_add_u64 v[220:221], s[90:91], 0, v[144:145]
	s_mov_b32 m0, s89
	v_lshl_add_u64 v[222:223], s[8:9], 0, v[146:147]
	global_load_lds_dwordx4 v[220:221], off
	v_lshl_add_u64 v[220:221], s[90:91], 0, v[146:147]
	s_add_i32 m0, s89, 0x2000
	s_nop 0
	global_load_lds_dwordx4 v[220:221], off
	v_lshl_add_u64 v[220:221], s[8:9], 0, v[144:145]
	s_mov_b32 m0, s44
	s_nop 0
	global_load_lds_dwordx4 v[220:221], off
	s_mov_b32 m0, s45
	s_nop 0
	global_load_lds_dwordx4 v[222:223], off
	s_waitcnt vmcnt(8)
	s_waitcnt lgkmcnt(0)
	s_barrier
	s_setprio 1
	s_waitcnt lgkmcnt(0)
	v_mfma_f32_16x16x32_bf16 v[60:63], v[128:131], v[184:187], v[60:63]
	v_mfma_f32_16x16x32_bf16 v[56:59], v[136:139], v[184:187], v[56:59]
	v_mfma_f32_16x16x32_bf16 v[44:47], v[128:131], v[192:195], v[44:47]
	v_mfma_f32_16x16x32_bf16 v[40:43], v[136:139], v[192:195], v[40:43]
	v_mfma_f32_16x16x32_bf16 v[28:31], v[128:131], v[200:203], v[28:31]
	v_mfma_f32_16x16x32_bf16 v[24:27], v[136:139], v[200:203], v[24:27]
	v_mfma_f32_16x16x32_bf16 v[12:15], v[128:131], v[208:211], v[12:15]
	v_mfma_f32_16x16x32_bf16 v[8:11], v[136:139], v[208:211], v[8:11]
	v_mfma_f32_16x16x32_bf16 v[60:63], v[132:135], v[188:191], v[60:63]
	v_mfma_f32_16x16x32_bf16 v[56:59], v[140:143], v[188:191], v[56:59]
	v_mfma_f32_16x16x32_bf16 v[44:47], v[132:135], v[196:199], v[44:47]
	v_mfma_f32_16x16x32_bf16 v[40:43], v[140:143], v[196:199], v[40:43]
	v_mfma_f32_16x16x32_bf16 v[28:31], v[132:135], v[204:207], v[28:31]
	v_mfma_f32_16x16x32_bf16 v[24:27], v[140:143], v[204:207], v[24:27]
	v_mfma_f32_16x16x32_bf16 v[12:15], v[132:135], v[212:215], v[12:15]
	v_mfma_f32_16x16x32_bf16 v[8:11], v[140:143], v[212:215], v[8:11]
	v_mfma_f32_16x16x32_bf16 v[52:55], v[162:165], v[184:187], v[52:55]
	v_mfma_f32_16x16x32_bf16 v[48:51], v[176:179], v[184:187], v[48:51]
	v_mfma_f32_16x16x32_bf16 v[36:39], v[162:165], v[192:195], v[36:39]
	v_mfma_f32_16x16x32_bf16 v[32:35], v[176:179], v[192:195], v[32:35]
	v_mfma_f32_16x16x32_bf16 v[20:23], v[162:165], v[200:203], v[20:23]
	v_mfma_f32_16x16x32_bf16 v[16:19], v[176:179], v[200:203], v[16:19]
	v_mfma_f32_16x16x32_bf16 v[4:7], v[162:165], v[208:211], v[4:7]
	v_mfma_f32_16x16x32_bf16 v[0:3], v[176:179], v[208:211], v[0:3]
	v_mfma_f32_16x16x32_bf16 v[52:55], v[166:169], v[188:191], v[52:55]
	v_mfma_f32_16x16x32_bf16 v[48:51], v[180:183], v[188:191], v[48:51]
	v_mfma_f32_16x16x32_bf16 v[36:39], v[166:169], v[196:199], v[36:39]
	v_mfma_f32_16x16x32_bf16 v[32:35], v[180:183], v[196:199], v[32:35]
	v_mfma_f32_16x16x32_bf16 v[20:23], v[166:169], v[204:207], v[20:23]
	v_mfma_f32_16x16x32_bf16 v[16:19], v[180:183], v[204:207], v[16:19]
	v_mfma_f32_16x16x32_bf16 v[4:7], v[166:169], v[212:215], v[4:7]
	v_mfma_f32_16x16x32_bf16 v[0:3], v[180:183], v[212:215], v[0:3]
	s_setprio 0
	s_barrier
	s_add_i32 s89, 0, 0x18000
	s_add_i32 s90, 0, 0x1c000
	v_add_u32_e32 v140, s89, v153
	v_add_u32_e32 v180, s90, v153
	ds_read_b128 v[128:131], v140
	ds_read_b128 v[132:135], v140 offset:1024
	ds_read_b128 v[136:139], v140 offset:2048
	ds_read_b128 v[140:143], v140 offset:3072
	ds_read_b128 v[162:165], v180
	ds_read_b128 v[166:169], v180 offset:1024
	ds_read_b128 v[176:179], v180 offset:2048
	ds_read_b128 v[180:183], v180 offset:3072
	s_add_u32 s8, s8, 0x80000
	s_addc_u32 s9, s9, 0
	s_mov_b32 m0, s46
	v_lshl_add_u64 v[224:225], s[8:9], 0, v[144:145]
	ds_read_b128 v[184:187], v175 offset:32768
	ds_read_b128 v[188:191], v175 offset:33792
	ds_read_b128 v[192:195], v175 offset:34816
	ds_read_b128 v[196:199], v175 offset:35840
	ds_read_b128 v[200:203], v175 offset:36864
	ds_read_b128 v[204:207], v175 offset:37888
	ds_read_b128 v[208:211], v175 offset:38912
	ds_read_b128 v[212:215], v175 offset:39936
	global_load_lds_dwordx4 v[224:225], off
	v_lshl_add_u64 v[224:225], s[8:9], 0, v[146:147]
	s_mov_b32 m0, s47
	s_nop 0
	global_load_lds_dwordx4 v[224:225], off
	s_waitcnt vmcnt(8)
	s_waitcnt lgkmcnt(0)
	s_barrier
	s_setprio 1
	s_waitcnt lgkmcnt(0)
	v_mfma_f32_16x16x32_bf16 v[124:127], v[128:131], v[184:187], v[124:127]
	v_mfma_f32_16x16x32_bf16 v[120:123], v[136:139], v[184:187], v[120:123]
	v_mfma_f32_16x16x32_bf16 v[108:111], v[128:131], v[192:195], v[108:111]
	v_mfma_f32_16x16x32_bf16 v[104:107], v[136:139], v[192:195], v[104:107]
	v_mfma_f32_16x16x32_bf16 v[92:95], v[128:131], v[200:203], v[92:95]
	v_mfma_f32_16x16x32_bf16 v[88:91], v[136:139], v[200:203], v[88:91]
	v_mfma_f32_16x16x32_bf16 v[76:79], v[128:131], v[208:211], v[76:79]
	v_mfma_f32_16x16x32_bf16 v[72:75], v[136:139], v[208:211], v[72:75]
	v_mfma_f32_16x16x32_bf16 v[124:127], v[132:135], v[188:191], v[124:127]
	v_mfma_f32_16x16x32_bf16 v[120:123], v[140:143], v[188:191], v[120:123]
	v_mfma_f32_16x16x32_bf16 v[108:111], v[132:135], v[196:199], v[108:111]
	v_mfma_f32_16x16x32_bf16 v[104:107], v[140:143], v[196:199], v[104:107]
	v_mfma_f32_16x16x32_bf16 v[92:95], v[132:135], v[204:207], v[92:95]
	v_mfma_f32_16x16x32_bf16 v[88:91], v[140:143], v[204:207], v[88:91]
	v_mfma_f32_16x16x32_bf16 v[76:79], v[132:135], v[212:215], v[76:79]
	v_mfma_f32_16x16x32_bf16 v[72:75], v[140:143], v[212:215], v[72:75]
	v_mfma_f32_16x16x32_bf16 v[116:119], v[162:165], v[184:187], v[116:119]
	v_mfma_f32_16x16x32_bf16 v[112:115], v[176:179], v[184:187], v[112:115]
	v_mfma_f32_16x16x32_bf16 v[100:103], v[162:165], v[192:195], v[100:103]
	v_mfma_f32_16x16x32_bf16 v[96:99], v[176:179], v[192:195], v[96:99]
	v_mfma_f32_16x16x32_bf16 v[84:87], v[162:165], v[200:203], v[84:87]
	v_mfma_f32_16x16x32_bf16 v[80:83], v[176:179], v[200:203], v[80:83]
	v_mfma_f32_16x16x32_bf16 v[68:71], v[162:165], v[208:211], v[68:71]
	v_mfma_f32_16x16x32_bf16 v[64:67], v[176:179], v[208:211], v[64:67]
	v_mfma_f32_16x16x32_bf16 v[116:119], v[166:169], v[188:191], v[116:119]
	v_mfma_f32_16x16x32_bf16 v[112:115], v[180:183], v[188:191], v[112:115]
	v_mfma_f32_16x16x32_bf16 v[100:103], v[166:169], v[196:199], v[100:103]
	v_mfma_f32_16x16x32_bf16 v[96:99], v[180:183], v[196:199], v[96:99]
	v_mfma_f32_16x16x32_bf16 v[84:87], v[166:169], v[204:207], v[84:87]
	v_mfma_f32_16x16x32_bf16 v[80:83], v[180:183], v[204:207], v[80:83]
	v_mfma_f32_16x16x32_bf16 v[68:71], v[166:169], v[212:215], v[68:71]
	v_mfma_f32_16x16x32_bf16 v[64:67], v[180:183], v[212:215], v[64:67]
	s_setprio 0
	s_barrier
	s_add_i32 s8, s89, s43
	v_lshl_add_u64 v[216:217], v[216:217], 0, s[72:73]
	s_mov_b32 m0, s8
	ds_read_b128 v[184:187], v175 offset:49152
	ds_read_b128 v[188:191], v175 offset:50176
	ds_read_b128 v[192:195], v175 offset:51200
	ds_read_b128 v[196:199], v175 offset:52224
	ds_read_b128 v[200:203], v175 offset:53248
	ds_read_b128 v[204:207], v175 offset:54272
	ds_read_b128 v[208:211], v175 offset:55296
	ds_read_b128 v[212:215], v175 offset:56320
	global_load_lds_dwordx4 v[216:217], off
	s_add_i32 m0, s8, 0x2000
	s_add_u32 s6, s6, 0x80080
	v_lshl_add_u64 v[216:217], v[218:219], 0, s[72:73]
	s_addc_u32 s7, s7, 0
	s_add_i32 s8, s90, s43
	global_load_lds_dwordx4 v[216:217], off
	v_lshl_add_u64 v[216:217], s[6:7], 0, v[144:145]
	s_mov_b32 m0, s8
	s_nop 0
	global_load_lds_dwordx4 v[216:217], off
	v_lshl_add_u64 v[216:217], s[6:7], 0, v[146:147]
	s_add_i32 m0, s8, 0x2000
	s_nop 0
	global_load_lds_dwordx4 v[216:217], off
	v_lshl_add_u64 v[216:217], v[220:221], 0, s[72:73]
	s_mov_b32 m0, s49
	s_nop 0
	global_load_lds_dwordx4 v[216:217], off
	v_lshl_add_u64 v[216:217], v[222:223], 0, s[72:73]
	s_mov_b32 m0, s50
	s_nop 0
	global_load_lds_dwordx4 v[216:217], off
	s_waitcnt vmcnt(8)
	s_waitcnt lgkmcnt(0)
	s_barrier
	s_setprio 1
	s_waitcnt lgkmcnt(0)
	v_mfma_f32_16x16x32_bf16 v[60:63], v[128:131], v[184:187], v[60:63]
	v_mfma_f32_16x16x32_bf16 v[56:59], v[136:139], v[184:187], v[56:59]
	v_mfma_f32_16x16x32_bf16 v[44:47], v[128:131], v[192:195], v[44:47]
	v_mfma_f32_16x16x32_bf16 v[40:43], v[136:139], v[192:195], v[40:43]
	v_mfma_f32_16x16x32_bf16 v[28:31], v[128:131], v[200:203], v[28:31]
	v_mfma_f32_16x16x32_bf16 v[24:27], v[136:139], v[200:203], v[24:27]
	v_mfma_f32_16x16x32_bf16 v[12:15], v[128:131], v[208:211], v[12:15]
	v_mfma_f32_16x16x32_bf16 v[8:11], v[136:139], v[208:211], v[8:11]
	v_mfma_f32_16x16x32_bf16 v[60:63], v[132:135], v[188:191], v[60:63]
	v_mfma_f32_16x16x32_bf16 v[56:59], v[140:143], v[188:191], v[56:59]
	v_mfma_f32_16x16x32_bf16 v[44:47], v[132:135], v[196:199], v[44:47]
	v_mfma_f32_16x16x32_bf16 v[40:43], v[140:143], v[196:199], v[40:43]
	v_mfma_f32_16x16x32_bf16 v[28:31], v[132:135], v[204:207], v[28:31]
	v_mfma_f32_16x16x32_bf16 v[24:27], v[140:143], v[204:207], v[24:27]
	v_mfma_f32_16x16x32_bf16 v[12:15], v[132:135], v[212:215], v[12:15]
	v_mfma_f32_16x16x32_bf16 v[8:11], v[140:143], v[212:215], v[8:11]
	v_mfma_f32_16x16x32_bf16 v[52:55], v[162:165], v[184:187], v[52:55]
	v_mfma_f32_16x16x32_bf16 v[48:51], v[176:179], v[184:187], v[48:51]
	v_mfma_f32_16x16x32_bf16 v[36:39], v[162:165], v[192:195], v[36:39]
	v_mfma_f32_16x16x32_bf16 v[32:35], v[176:179], v[192:195], v[32:35]
	v_mfma_f32_16x16x32_bf16 v[20:23], v[162:165], v[200:203], v[20:23]
	v_mfma_f32_16x16x32_bf16 v[16:19], v[176:179], v[200:203], v[16:19]
	v_mfma_f32_16x16x32_bf16 v[4:7], v[162:165], v[208:211], v[4:7]
	v_mfma_f32_16x16x32_bf16 v[0:3], v[176:179], v[208:211], v[0:3]
	v_mfma_f32_16x16x32_bf16 v[52:55], v[166:169], v[188:191], v[52:55]
	v_mfma_f32_16x16x32_bf16 v[48:51], v[180:183], v[188:191], v[48:51]
	v_mfma_f32_16x16x32_bf16 v[36:39], v[166:169], v[196:199], v[36:39]
	v_mfma_f32_16x16x32_bf16 v[32:35], v[180:183], v[196:199], v[32:35]
	v_mfma_f32_16x16x32_bf16 v[20:23], v[166:169], v[204:207], v[20:23]
	v_mfma_f32_16x16x32_bf16 v[16:19], v[180:183], v[204:207], v[16:19]
	v_mfma_f32_16x16x32_bf16 v[4:7], v[166:169], v[212:215], v[4:7]
	v_mfma_f32_16x16x32_bf16 v[0:3], v[180:183], v[212:215], v[0:3]
	s_setprio 0
	s_barrier
	s_add_i32 s85, s85, 2
	s_add_u32 s4, s4, 0x100
	s_addc_u32 s5, s5, 0
	s_add_u32 s77, s77, 0x100
	s_addc_u32 s84, s84, 0
	s_cmp_gt_u32 s85, 29
	s_cbranch_scc0 .LBB0_468
	s_and_b64 vcc, exec, s[74:75]
	s_cbranch_vccz .LBB0_471
	s_barrier

.LBB0_797:
	ds_read_b128 v[152:155], v146
	ds_read_b128 v[156:159], v146 offset:1024
	ds_read_b128 v[160:163], v146 offset:2048
	ds_read_b128 v[164:167], v146 offset:3072
	ds_read_b128 v[168:171], v147
	ds_read_b128 v[172:175], v147 offset:1024
	ds_read_b128 v[176:179], v147 offset:2048
	ds_read_b128 v[180:183], v147 offset:3072
	s_add_u32 s22, s20, 0xf8980080
	s_addc_u32 s23, s21, -1
	s_cmp_lg_u32 s46, 28
	s_cselect_b32 s22, s22, 0
	s_cselect_b32 s23, s23, 0
	s_add_u32 s24, s12, s22
	s_addc_u32 s25, s13, s23
	s_add_u32 s22, s6, s22
	s_addc_u32 s23, s7, s23
	s_mov_b32 m0, s47
	v_lshl_add_u64 v[216:217], v[138:139], 0, s[20:21]
	ds_read_b128 v[184:187], v148
	ds_read_b128 v[188:191], v148 offset:1024
	ds_read_b128 v[192:195], v148 offset:2048
	ds_read_b128 v[196:199], v148 offset:3072
	ds_read_b128 v[200:203], v148 offset:4096
	ds_read_b128 v[204:207], v148 offset:5120
	ds_read_b128 v[208:211], v148 offset:6144
	ds_read_b128 v[212:215], v148 offset:7168
	global_load_lds_dwordx4 v[216:217], off
	v_lshl_add_u64 v[216:217], v[140:141], 0, s[20:21]
	s_mov_b32 m0, s48
	s_nop 0
	global_load_lds_dwordx4 v[216:217], off
	s_waitcnt vmcnt(8)
	s_waitcnt lgkmcnt(0)
	s_barrier
	s_setprio 1
	s_waitcnt lgkmcnt(0)
	v_mfma_f32_16x16x32_bf16 v[124:127], v[152:155], v[184:187], v[124:127]
	v_mfma_f32_16x16x32_bf16 v[120:123], v[160:163], v[184:187], v[120:123]
	v_mfma_f32_16x16x32_bf16 v[108:111], v[152:155], v[192:195], v[108:111]
	v_mfma_f32_16x16x32_bf16 v[104:107], v[160:163], v[192:195], v[104:107]
	v_mfma_f32_16x16x32_bf16 v[92:95], v[152:155], v[200:203], v[92:95]
	v_mfma_f32_16x16x32_bf16 v[88:91], v[160:163], v[200:203], v[88:91]
	v_mfma_f32_16x16x32_bf16 v[76:79], v[152:155], v[208:211], v[76:79]
	v_mfma_f32_16x16x32_bf16 v[72:75], v[160:163], v[208:211], v[72:75]
	v_mfma_f32_16x16x32_bf16 v[124:127], v[156:159], v[188:191], v[124:127]
	v_mfma_f32_16x16x32_bf16 v[120:123], v[164:167], v[188:191], v[120:123]
	v_mfma_f32_16x16x32_bf16 v[108:111], v[156:159], v[196:199], v[108:111]
	v_mfma_f32_16x16x32_bf16 v[104:107], v[164:167], v[196:199], v[104:107]
	v_mfma_f32_16x16x32_bf16 v[92:95], v[156:159], v[204:207], v[92:95]
	v_mfma_f32_16x16x32_bf16 v[88:91], v[164:167], v[204:207], v[88:91]
	v_mfma_f32_16x16x32_bf16 v[76:79], v[156:159], v[212:215], v[76:79]
	v_mfma_f32_16x16x32_bf16 v[72:75], v[164:167], v[212:215], v[72:75]
	v_mfma_f32_16x16x32_bf16 v[116:119], v[168:171], v[184:187], v[116:119]
	v_mfma_f32_16x16x32_bf16 v[112:115], v[176:179], v[184:187], v[112:115]
	v_mfma_f32_16x16x32_bf16 v[100:103], v[168:171], v[192:195], v[100:103]
	v_mfma_f32_16x16x32_bf16 v[96:99], v[176:179], v[192:195], v[96:99]
	v_mfma_f32_16x16x32_bf16 v[84:87], v[168:171], v[200:203], v[84:87]
	v_mfma_f32_16x16x32_bf16 v[80:83], v[176:179], v[200:203], v[80:83]
	v_mfma_f32_16x16x32_bf16 v[68:71], v[168:171], v[208:211], v[68:71]
	v_mfma_f32_16x16x32_bf16 v[64:67], v[176:179], v[208:211], v[64:67]
	v_mfma_f32_16x16x32_bf16 v[116:119], v[172:175], v[188:191], v[116:119]
	v_mfma_f32_16x16x32_bf16 v[112:115], v[180:183], v[188:191], v[112:115]
	v_mfma_f32_16x16x32_bf16 v[100:103], v[172:175], v[196:199], v[100:103]
	v_mfma_f32_16x16x32_bf16 v[96:99], v[180:183], v[196:199], v[96:99]
	v_mfma_f32_16x16x32_bf16 v[84:87], v[172:175], v[204:207], v[84:87]
	v_mfma_f32_16x16x32_bf16 v[80:83], v[180:183], v[204:207], v[80:83]
	v_mfma_f32_16x16x32_bf16 v[68:71], v[172:175], v[212:215], v[68:71]
	v_mfma_f32_16x16x32_bf16 v[64:67], v[180:183], v[212:215], v[64:67]
	s_setprio 0
	s_barrier
	s_mov_b32 m0, s49
	v_lshl_add_u64 v[216:217], s[22:23], 0, v[128:129]
	s_add_u32 s86, s22, 0x80000
	ds_read_b128 v[184:187], v148 offset:16384
	ds_read_b128 v[188:191], v148 offset:17408
	ds_read_b128 v[192:195], v148 offset:18432
	ds_read_b128 v[196:199], v148 offset:19456
	ds_read_b128 v[200:203], v148 offset:20480
	ds_read_b128 v[204:207], v148 offset:21504
	ds_read_b128 v[208:211], v148 offset:22528
	ds_read_b128 v[212:215], v148 offset:23552
	global_load_lds_dwordx4 v[216:217], off
	v_lshl_add_u64 v[218:219], s[22:23], 0, v[130:131]
	s_mov_b32 m0, s50
	s_addc_u32 s87, s23, 0
	global_load_lds_dwordx4 v[218:219], off
	v_lshl_add_u64 v[220:221], s[86:87], 0, v[128:129]
	s_mov_b32 m0, s51
	v_lshl_add_u64 v[222:223], s[24:25], 0, v[130:131]
	global_load_lds_dwordx4 v[220:221], off
	v_lshl_add_u64 v[220:221], s[86:87], 0, v[130:131]
	s_mov_b32 m0, s56
	s_nop 0
	global_load_lds_dwordx4 v[220:221], off
	v_lshl_add_u64 v[220:221], s[24:25], 0, v[128:129]
	s_mov_b32 m0, s5
	s_nop 0
	global_load_lds_dwordx4 v[220:221], off
	s_mov_b32 m0, s39
	s_nop 0
	global_load_lds_dwordx4 v[222:223], off
	s_waitcnt vmcnt(8)
	s_waitcnt lgkmcnt(0)
	s_barrier
	s_setprio 1
	s_waitcnt lgkmcnt(0)
	v_mfma_f32_16x16x32_bf16 v[60:63], v[152:155], v[184:187], v[60:63]
	v_mfma_f32_16x16x32_bf16 v[56:59], v[160:163], v[184:187], v[56:59]
	v_mfma_f32_16x16x32_bf16 v[44:47], v[152:155], v[192:195], v[44:47]
	v_mfma_f32_16x16x32_bf16 v[40:43], v[160:163], v[192:195], v[40:43]
	v_mfma_f32_16x16x32_bf16 v[28:31], v[152:155], v[200:203], v[28:31]
	v_mfma_f32_16x16x32_bf16 v[24:27], v[160:163], v[200:203], v[24:27]
	v_mfma_f32_16x16x32_bf16 v[12:15], v[152:155], v[208:211], v[12:15]
	v_mfma_f32_16x16x32_bf16 v[8:11], v[160:163], v[208:211], v[8:11]
	v_mfma_f32_16x16x32_bf16 v[60:63], v[156:159], v[188:191], v[60:63]
	v_mfma_f32_16x16x32_bf16 v[56:59], v[164:167], v[188:191], v[56:59]
	v_mfma_f32_16x16x32_bf16 v[44:47], v[156:159], v[196:199], v[44:47]
	v_mfma_f32_16x16x32_bf16 v[40:43], v[164:167], v[196:199], v[40:43]
	v_mfma_f32_16x16x32_bf16 v[28:31], v[156:159], v[204:207], v[28:31]
	v_mfma_f32_16x16x32_bf16 v[24:27], v[164:167], v[204:207], v[24:27]
	v_mfma_f32_16x16x32_bf16 v[12:15], v[156:159], v[212:215], v[12:15]
	v_mfma_f32_16x16x32_bf16 v[8:11], v[164:167], v[212:215], v[8:11]
	v_mfma_f32_16x16x32_bf16 v[52:55], v[168:171], v[184:187], v[52:55]
	v_mfma_f32_16x16x32_bf16 v[48:51], v[176:179], v[184:187], v[48:51]
	v_mfma_f32_16x16x32_bf16 v[36:39], v[168:171], v[192:195], v[36:39]
	v_mfma_f32_16x16x32_bf16 v[32:35], v[176:179], v[192:195], v[32:35]
	v_mfma_f32_16x16x32_bf16 v[20:23], v[168:171], v[200:203], v[20:23]
	v_mfma_f32_16x16x32_bf16 v[16:19], v[176:179], v[200:203], v[16:19]
	v_mfma_f32_16x16x32_bf16 v[4:7], v[168:171], v[208:211], v[4:7]
	v_mfma_f32_16x16x32_bf16 v[0:3], v[176:179], v[208:211], v[0:3]
	v_mfma_f32_16x16x32_bf16 v[52:55], v[172:175], v[188:191], v[52:55]
	v_mfma_f32_16x16x32_bf16 v[48:51], v[180:183], v[188:191], v[48:51]
	v_mfma_f32_16x16x32_bf16 v[36:39], v[172:175], v[196:199], v[36:39]
	v_mfma_f32_16x16x32_bf16 v[32:35], v[180:183], v[196:199], v[32:35]
	v_mfma_f32_16x16x32_bf16 v[20:23], v[172:175], v[204:207], v[20:23]
	v_mfma_f32_16x16x32_bf16 v[16:19], v[180:183], v[204:207], v[16:19]
	v_mfma_f32_16x16x32_bf16 v[4:7], v[172:175], v[212:215], v[4:7]
	v_mfma_f32_16x16x32_bf16 v[0:3], v[180:183], v[212:215], v[0:3]
	s_setprio 0
	s_barrier
	ds_read_b128 v[152:155], v149
	ds_read_b128 v[156:159], v149 offset:1024
	ds_read_b128 v[160:163], v149 offset:2048
	ds_read_b128 v[164:167], v149 offset:3072
	ds_read_b128 v[168:171], v150
	ds_read_b128 v[172:175], v150 offset:1024
	ds_read_b128 v[176:179], v150 offset:2048
	ds_read_b128 v[180:183], v150 offset:3072
	s_add_u32 s24, s24, 0x80000
	s_addc_u32 s25, s25, 0
	s_mov_b32 m0, s40
	v_lshl_add_u64 v[224:225], s[24:25], 0, v[128:129]
	ds_read_b128 v[184:187], v148 offset:32768
	ds_read_b128 v[188:191], v148 offset:33792
	ds_read_b128 v[192:195], v148 offset:34816
	ds_read_b128 v[196:199], v148 offset:35840
	ds_read_b128 v[200:203], v148 offset:36864
	ds_read_b128 v[204:207], v148 offset:37888
	ds_read_b128 v[208:211], v148 offset:38912
	ds_read_b128 v[212:215], v148 offset:39936
	global_load_lds_dwordx4 v[224:225], off
	v_lshl_add_u64 v[224:225], s[24:25], 0, v[130:131]
	s_mov_b32 m0, s42
	s_nop 0
	global_load_lds_dwordx4 v[224:225], off
	s_waitcnt vmcnt(8)
	s_waitcnt lgkmcnt(0)
	s_barrier
	s_setprio 1
	s_waitcnt lgkmcnt(0)
	v_mfma_f32_16x16x32_bf16 v[124:127], v[152:155], v[184:187], v[124:127]
	v_mfma_f32_16x16x32_bf16 v[120:123], v[160:163], v[184:187], v[120:123]
	v_mfma_f32_16x16x32_bf16 v[108:111], v[152:155], v[192:195], v[108:111]
	v_mfma_f32_16x16x32_bf16 v[104:107], v[160:163], v[192:195], v[104:107]
	v_mfma_f32_16x16x32_bf16 v[92:95], v[152:155], v[200:203], v[92:95]
	v_mfma_f32_16x16x32_bf16 v[88:91], v[160:163], v[200:203], v[88:91]
	v_mfma_f32_16x16x32_bf16 v[76:79], v[152:155], v[208:211], v[76:79]
	v_mfma_f32_16x16x32_bf16 v[72:75], v[160:163], v[208:211], v[72:75]
	v_mfma_f32_16x16x32_bf16 v[124:127], v[156:159], v[188:191], v[124:127]
	v_mfma_f32_16x16x32_bf16 v[120:123], v[164:167], v[188:191], v[120:123]
	v_mfma_f32_16x16x32_bf16 v[108:111], v[156:159], v[196:199], v[108:111]
	v_mfma_f32_16x16x32_bf16 v[104:107], v[164:167], v[196:199], v[104:107]
	v_mfma_f32_16x16x32_bf16 v[92:95], v[156:159], v[204:207], v[92:95]
	v_mfma_f32_16x16x32_bf16 v[88:91], v[164:167], v[204:207], v[88:91]
	v_mfma_f32_16x16x32_bf16 v[76:79], v[156:159], v[212:215], v[76:79]
	v_mfma_f32_16x16x32_bf16 v[72:75], v[164:167], v[212:215], v[72:75]
	v_mfma_f32_16x16x32_bf16 v[116:119], v[168:171], v[184:187], v[116:119]
	v_mfma_f32_16x16x32_bf16 v[112:115], v[176:179], v[184:187], v[112:115]
	v_mfma_f32_16x16x32_bf16 v[100:103], v[168:171], v[192:195], v[100:103]
	v_mfma_f32_16x16x32_bf16 v[96:99], v[176:179], v[192:195], v[96:99]
	v_mfma_f32_16x16x32_bf16 v[84:87], v[168:171], v[200:203], v[84:87]
	v_mfma_f32_16x16x32_bf16 v[80:83], v[176:179], v[200:203], v[80:83]
	v_mfma_f32_16x16x32_bf16 v[68:71], v[168:171], v[208:211], v[68:71]
	v_mfma_f32_16x16x32_bf16 v[64:67], v[176:179], v[208:211], v[64:67]
	v_mfma_f32_16x16x32_bf16 v[116:119], v[172:175], v[188:191], v[116:119]
	v_mfma_f32_16x16x32_bf16 v[112:115], v[180:183], v[188:191], v[112:115]
	v_mfma_f32_16x16x32_bf16 v[100:103], v[172:175], v[196:199], v[100:103]
	v_mfma_f32_16x16x32_bf16 v[96:99], v[180:183], v[196:199], v[96:99]
	v_mfma_f32_16x16x32_bf16 v[84:87], v[172:175], v[204:207], v[84:87]
	v_mfma_f32_16x16x32_bf16 v[80:83], v[180:183], v[204:207], v[80:83]
	v_mfma_f32_16x16x32_bf16 v[68:71], v[172:175], v[212:215], v[68:71]
	v_mfma_f32_16x16x32_bf16 v[64:67], v[180:183], v[212:215], v[64:67]
	s_setprio 0
	s_barrier
	s_mov_b32 m0, s57
	v_lshl_add_u64 v[216:217], v[216:217], 0, s[2:3]
	s_add_u32 s22, s22, 0x80080
	ds_read_b128 v[184:187], v148 offset:49152
	ds_read_b128 v[188:191], v148 offset:50176
	ds_read_b128 v[192:195], v148 offset:51200
	ds_read_b128 v[196:199], v148 offset:52224
	ds_read_b128 v[200:203], v148 offset:53248
	ds_read_b128 v[204:207], v148 offset:54272
	ds_read_b128 v[208:211], v148 offset:55296
	ds_read_b128 v[212:215], v148 offset:56320
	global_load_lds_dwordx4 v[216:217], off
	v_lshl_add_u64 v[216:217], v[218:219], 0, s[2:3]
	s_mov_b32 m0, s58
	s_addc_u32 s23, s23, 0
	global_load_lds_dwordx4 v[216:217], off
	v_lshl_add_u64 v[216:217], s[22:23], 0, v[128:129]
	s_mov_b32 m0, s59
	s_nop 0
	global_load_lds_dwordx4 v[216:217], off
	v_lshl_add_u64 v[216:217], s[22:23], 0, v[130:131]
	s_mov_b32 m0, s84
	s_nop 0
	global_load_lds_dwordx4 v[216:217], off
	v_lshl_add_u64 v[216:217], v[220:221], 0, s[2:3]
	s_mov_b32 m0, s44
	s_nop 0
	global_load_lds_dwordx4 v[216:217], off
	v_lshl_add_u64 v[216:217], v[222:223], 0, s[2:3]
	s_mov_b32 m0, s45
	s_nop 0
	global_load_lds_dwordx4 v[216:217], off
	s_waitcnt vmcnt(8)
	s_waitcnt lgkmcnt(0)
	s_barrier
	s_setprio 1
	s_waitcnt lgkmcnt(0)
	v_mfma_f32_16x16x32_bf16 v[60:63], v[152:155], v[184:187], v[60:63]
	v_mfma_f32_16x16x32_bf16 v[56:59], v[160:163], v[184:187], v[56:59]
	v_mfma_f32_16x16x32_bf16 v[44:47], v[152:155], v[192:195], v[44:47]
	v_mfma_f32_16x16x32_bf16 v[40:43], v[160:163], v[192:195], v[40:43]
	v_mfma_f32_16x16x32_bf16 v[28:31], v[152:155], v[200:203], v[28:31]
	v_mfma_f32_16x16x32_bf16 v[24:27], v[160:163], v[200:203], v[24:27]
	v_mfma_f32_16x16x32_bf16 v[12:15], v[152:155], v[208:211], v[12:15]
	v_mfma_f32_16x16x32_bf16 v[8:11], v[160:163], v[208:211], v[8:11]
	v_mfma_f32_16x16x32_bf16 v[60:63], v[156:159], v[188:191], v[60:63]
	v_mfma_f32_16x16x32_bf16 v[56:59], v[164:167], v[188:191], v[56:59]
	v_mfma_f32_16x16x32_bf16 v[44:47], v[156:159], v[196:199], v[44:47]
	v_mfma_f32_16x16x32_bf16 v[40:43], v[164:167], v[196:199], v[40:43]
	v_mfma_f32_16x16x32_bf16 v[28:31], v[156:159], v[204:207], v[28:31]
	v_mfma_f32_16x16x32_bf16 v[24:27], v[164:167], v[204:207], v[24:27]
	v_mfma_f32_16x16x32_bf16 v[12:15], v[156:159], v[212:215], v[12:15]
	v_mfma_f32_16x16x32_bf16 v[8:11], v[164:167], v[212:215], v[8:11]
	v_mfma_f32_16x16x32_bf16 v[52:55], v[168:171], v[184:187], v[52:55]
	v_mfma_f32_16x16x32_bf16 v[48:51], v[176:179], v[184:187], v[48:51]
	v_mfma_f32_16x16x32_bf16 v[36:39], v[168:171], v[192:195], v[36:39]
	v_mfma_f32_16x16x32_bf16 v[32:35], v[176:179], v[192:195], v[32:35]
	v_mfma_f32_16x16x32_bf16 v[20:23], v[168:171], v[200:203], v[20:23]
	v_mfma_f32_16x16x32_bf16 v[16:19], v[176:179], v[200:203], v[16:19]
	v_mfma_f32_16x16x32_bf16 v[4:7], v[168:171], v[208:211], v[4:7]
	v_mfma_f32_16x16x32_bf16 v[0:3], v[176:179], v[208:211], v[0:3]
	v_mfma_f32_16x16x32_bf16 v[52:55], v[172:175], v[188:191], v[52:55]
	v_mfma_f32_16x16x32_bf16 v[48:51], v[180:183], v[188:191], v[48:51]
	v_mfma_f32_16x16x32_bf16 v[36:39], v[172:175], v[196:199], v[36:39]
	v_mfma_f32_16x16x32_bf16 v[32:35], v[180:183], v[196:199], v[32:35]
	v_mfma_f32_16x16x32_bf16 v[20:23], v[172:175], v[204:207], v[20:23]
	v_mfma_f32_16x16x32_bf16 v[16:19], v[180:183], v[204:207], v[16:19]
	v_mfma_f32_16x16x32_bf16 v[4:7], v[172:175], v[212:215], v[4:7]
	v_mfma_f32_16x16x32_bf16 v[0:3], v[180:183], v[212:215], v[0:3]
	s_setprio 0
	s_barrier
	s_add_i32 s46, s46, 2
	s_add_u32 s20, s20, 0x100
	s_addc_u32 s21, s21, 0
	s_cmp_gt_u32 s46, 29
	s_cbranch_scc0 .LBB0_797
	s_cmpk_lt_u32 s38, 0x100
	s_cbranch_scc0 .LBB0_800
	s_barrier

.LBB0_1058:
	ds_read_b128 v[136:139], v143
	ds_read_b128 v[146:149], v143 offset:1024
	ds_read_b128 v[150:153], v143 offset:2048
	ds_read_b128 v[154:157], v143 offset:3072
	ds_read_b128 v[158:161], v144
	ds_read_b128 v[162:165], v144 offset:1024
	ds_read_b128 v[166:169], v144 offset:2048
	ds_read_b128 v[170:173], v144 offset:3072
	s_add_u32 s26, s24, 0xfffc0080
	s_addc_u32 s27, s25, -1
	s_cmp_eq_u32 s56, 12
	s_cselect_b32 s29, s46, s27
	s_cselect_b32 s28, s47, s26
	s_cselect_b32 s27, s48, s51
	s_cselect_b32 s26, s49, s50
	v_lshl_add_u64 v[206:207], s[24:25], 0, v[132:133]
	s_add_i32 m0, s35, 0xc000
	ds_read_b128 v[174:177], v145
	ds_read_b128 v[178:181], v145 offset:1024
	ds_read_b128 v[182:185], v145 offset:2048
	ds_read_b128 v[186:189], v145 offset:3072
	ds_read_b128 v[190:193], v145 offset:4096
	ds_read_b128 v[194:197], v145 offset:5120
	ds_read_b128 v[198:201], v145 offset:6144
	ds_read_b128 v[202:205], v145 offset:7168
	global_load_lds_dwordx4 v[206:207], off
	v_lshl_add_u64 v[206:207], s[24:25], 0, v[134:135]
	s_add_i32 m0, s35, 0xe000
	s_nop 0
	global_load_lds_dwordx4 v[206:207], off
	s_waitcnt vmcnt(8)
	s_waitcnt lgkmcnt(0)
	s_barrier
	s_setprio 1
	s_waitcnt lgkmcnt(0)
	v_mfma_f32_16x16x32_bf16 v[124:127], v[136:139], v[174:177], v[124:127]
	v_mfma_f32_16x16x32_bf16 v[120:123], v[150:153], v[174:177], v[120:123]
	v_mfma_f32_16x16x32_bf16 v[108:111], v[136:139], v[182:185], v[108:111]
	v_mfma_f32_16x16x32_bf16 v[104:107], v[150:153], v[182:185], v[104:107]
	v_mfma_f32_16x16x32_bf16 v[92:95], v[136:139], v[190:193], v[92:95]
	v_mfma_f32_16x16x32_bf16 v[88:91], v[150:153], v[190:193], v[88:91]
	v_mfma_f32_16x16x32_bf16 v[76:79], v[136:139], v[198:201], v[76:79]
	v_mfma_f32_16x16x32_bf16 v[72:75], v[150:153], v[198:201], v[72:75]
	v_mfma_f32_16x16x32_bf16 v[124:127], v[146:149], v[178:181], v[124:127]
	v_mfma_f32_16x16x32_bf16 v[120:123], v[154:157], v[178:181], v[120:123]
	v_mfma_f32_16x16x32_bf16 v[108:111], v[146:149], v[186:189], v[108:111]
	v_mfma_f32_16x16x32_bf16 v[104:107], v[154:157], v[186:189], v[104:107]
	v_mfma_f32_16x16x32_bf16 v[92:95], v[146:149], v[194:197], v[92:95]
	v_mfma_f32_16x16x32_bf16 v[88:91], v[154:157], v[194:197], v[88:91]
	v_mfma_f32_16x16x32_bf16 v[76:79], v[146:149], v[202:205], v[76:79]
	v_mfma_f32_16x16x32_bf16 v[72:75], v[154:157], v[202:205], v[72:75]
	v_mfma_f32_16x16x32_bf16 v[116:119], v[158:161], v[174:177], v[116:119]
	v_mfma_f32_16x16x32_bf16 v[112:115], v[166:169], v[174:177], v[112:115]
	v_mfma_f32_16x16x32_bf16 v[100:103], v[158:161], v[182:185], v[100:103]
	v_mfma_f32_16x16x32_bf16 v[96:99], v[166:169], v[182:185], v[96:99]
	v_mfma_f32_16x16x32_bf16 v[84:87], v[158:161], v[190:193], v[84:87]
	v_mfma_f32_16x16x32_bf16 v[80:83], v[166:169], v[190:193], v[80:83]
	v_mfma_f32_16x16x32_bf16 v[68:71], v[158:161], v[198:201], v[68:71]
	v_mfma_f32_16x16x32_bf16 v[64:67], v[166:169], v[198:201], v[64:67]
	v_mfma_f32_16x16x32_bf16 v[116:119], v[162:165], v[178:181], v[116:119]
	v_mfma_f32_16x16x32_bf16 v[112:115], v[170:173], v[178:181], v[112:115]
	v_mfma_f32_16x16x32_bf16 v[100:103], v[162:165], v[186:189], v[100:103]
	v_mfma_f32_16x16x32_bf16 v[96:99], v[170:173], v[186:189], v[96:99]
	v_mfma_f32_16x16x32_bf16 v[84:87], v[162:165], v[194:197], v[84:87]
	v_mfma_f32_16x16x32_bf16 v[80:83], v[170:173], v[194:197], v[80:83]
	v_mfma_f32_16x16x32_bf16 v[68:71], v[162:165], v[202:205], v[68:71]
	v_mfma_f32_16x16x32_bf16 v[64:67], v[170:173], v[202:205], v[64:67]
	s_setprio 0
	s_barrier
	s_add_i32 s57, s42, s33
	v_lshl_add_u64 v[206:207], s[26:27], 0, v[130:131]
	s_mov_b32 m0, s57
	ds_read_b128 v[174:177], v145 offset:16384
	ds_read_b128 v[178:181], v145 offset:17408
	ds_read_b128 v[182:185], v145 offset:18432
	ds_read_b128 v[186:189], v145 offset:19456
	ds_read_b128 v[190:193], v145 offset:20480
	ds_read_b128 v[194:197], v145 offset:21504
	ds_read_b128 v[198:201], v145 offset:22528
	ds_read_b128 v[202:205], v145 offset:23552
	global_load_lds_dwordx4 v[206:207], off
	s_add_i32 m0, s57, 0x2000
	s_add_u32 s58, s26, 0x40000
	v_lshl_add_u64 v[208:209], s[26:27], 0, v[128:129]
	s_addc_u32 s59, s27, 0
	s_add_i32 s57, s43, s33
	global_load_lds_dwordx4 v[208:209], off
	v_lshl_add_u64 v[210:211], s[58:59], 0, v[130:131]
	s_mov_b32 m0, s57
	v_lshl_add_u64 v[212:213], s[28:29], 0, v[128:129]
	global_load_lds_dwordx4 v[210:211], off
	v_lshl_add_u64 v[210:211], s[58:59], 0, v[128:129]
	s_add_i32 m0, s57, 0x2000
	s_nop 0
	global_load_lds_dwordx4 v[210:211], off
	v_lshl_add_u64 v[210:211], s[28:29], 0, v[130:131]
	s_mov_b32 m0, s35
	s_nop 0
	global_load_lds_dwordx4 v[210:211], off
	s_mov_b32 m0, s36
	s_nop 0
	global_load_lds_dwordx4 v[212:213], off
	s_waitcnt vmcnt(8)
	s_waitcnt lgkmcnt(0)
	s_barrier
	s_setprio 1
	s_waitcnt lgkmcnt(0)
	v_mfma_f32_16x16x32_bf16 v[60:63], v[136:139], v[174:177], v[60:63]
	v_mfma_f32_16x16x32_bf16 v[56:59], v[150:153], v[174:177], v[56:59]
	v_mfma_f32_16x16x32_bf16 v[44:47], v[136:139], v[182:185], v[44:47]
	v_mfma_f32_16x16x32_bf16 v[40:43], v[150:153], v[182:185], v[40:43]
	v_mfma_f32_16x16x32_bf16 v[28:31], v[136:139], v[190:193], v[28:31]
	v_mfma_f32_16x16x32_bf16 v[24:27], v[150:153], v[190:193], v[24:27]
	v_mfma_f32_16x16x32_bf16 v[12:15], v[136:139], v[198:201], v[12:15]
	v_mfma_f32_16x16x32_bf16 v[8:11], v[150:153], v[198:201], v[8:11]
	v_mfma_f32_16x16x32_bf16 v[60:63], v[146:149], v[178:181], v[60:63]
	v_mfma_f32_16x16x32_bf16 v[56:59], v[154:157], v[178:181], v[56:59]
	v_mfma_f32_16x16x32_bf16 v[44:47], v[146:149], v[186:189], v[44:47]
	v_mfma_f32_16x16x32_bf16 v[40:43], v[154:157], v[186:189], v[40:43]
	v_mfma_f32_16x16x32_bf16 v[28:31], v[146:149], v[194:197], v[28:31]
	v_mfma_f32_16x16x32_bf16 v[24:27], v[154:157], v[194:197], v[24:27]
	v_mfma_f32_16x16x32_bf16 v[12:15], v[146:149], v[202:205], v[12:15]
	v_mfma_f32_16x16x32_bf16 v[8:11], v[154:157], v[202:205], v[8:11]
	v_mfma_f32_16x16x32_bf16 v[52:55], v[158:161], v[174:177], v[52:55]
	v_mfma_f32_16x16x32_bf16 v[48:51], v[166:169], v[174:177], v[48:51]
	v_mfma_f32_16x16x32_bf16 v[36:39], v[158:161], v[182:185], v[36:39]
	v_mfma_f32_16x16x32_bf16 v[32:35], v[166:169], v[182:185], v[32:35]
	v_mfma_f32_16x16x32_bf16 v[20:23], v[158:161], v[190:193], v[20:23]
	v_mfma_f32_16x16x32_bf16 v[16:19], v[166:169], v[190:193], v[16:19]
	v_mfma_f32_16x16x32_bf16 v[4:7], v[158:161], v[198:201], v[4:7]
	v_mfma_f32_16x16x32_bf16 v[0:3], v[166:169], v[198:201], v[0:3]
	v_mfma_f32_16x16x32_bf16 v[52:55], v[162:165], v[178:181], v[52:55]
	v_mfma_f32_16x16x32_bf16 v[48:51], v[170:173], v[178:181], v[48:51]
	v_mfma_f32_16x16x32_bf16 v[36:39], v[162:165], v[186:189], v[36:39]
	v_mfma_f32_16x16x32_bf16 v[32:35], v[170:173], v[186:189], v[32:35]
	v_mfma_f32_16x16x32_bf16 v[20:23], v[162:165], v[194:197], v[20:23]
	v_mfma_f32_16x16x32_bf16 v[16:19], v[170:173], v[194:197], v[16:19]
	v_mfma_f32_16x16x32_bf16 v[4:7], v[162:165], v[202:205], v[4:7]
	v_mfma_f32_16x16x32_bf16 v[0:3], v[170:173], v[202:205], v[0:3]
	s_setprio 0
	s_barrier
	s_add_i32 s57, 0, 0x18000
	s_add_i32 s58, 0, 0x1c000
	v_add_u32_e32 v154, s57, v141
	v_add_u32_e32 v170, s58, v141
	ds_read_b128 v[136:139], v154
	ds_read_b128 v[146:149], v154 offset:1024
	ds_read_b128 v[150:153], v154 offset:2048
	ds_read_b128 v[154:157], v154 offset:3072
	ds_read_b128 v[158:161], v170
	ds_read_b128 v[162:165], v170 offset:1024
	ds_read_b128 v[166:169], v170 offset:2048
	ds_read_b128 v[170:173], v170 offset:3072
	s_add_u32 s28, s28, 0x40000
	s_addc_u32 s29, s29, 0
	s_mov_b32 m0, s37
	v_lshl_add_u64 v[214:215], s[28:29], 0, v[130:131]
	ds_read_b128 v[174:177], v145 offset:32768
	ds_read_b128 v[178:181], v145 offset:33792
	ds_read_b128 v[182:185], v145 offset:34816
	ds_read_b128 v[186:189], v145 offset:35840
	ds_read_b128 v[190:193], v145 offset:36864
	ds_read_b128 v[194:197], v145 offset:37888
	ds_read_b128 v[198:201], v145 offset:38912
	ds_read_b128 v[202:205], v145 offset:39936
	global_load_lds_dwordx4 v[214:215], off
	v_lshl_add_u64 v[214:215], s[28:29], 0, v[128:129]
	s_mov_b32 m0, s38
	s_nop 0
	global_load_lds_dwordx4 v[214:215], off
	s_waitcnt vmcnt(8)
	s_waitcnt lgkmcnt(0)
	s_barrier
	s_setprio 1
	s_waitcnt lgkmcnt(0)
	v_mfma_f32_16x16x32_bf16 v[124:127], v[136:139], v[174:177], v[124:127]
	v_mfma_f32_16x16x32_bf16 v[120:123], v[150:153], v[174:177], v[120:123]
	v_mfma_f32_16x16x32_bf16 v[108:111], v[136:139], v[182:185], v[108:111]
	v_mfma_f32_16x16x32_bf16 v[104:107], v[150:153], v[182:185], v[104:107]
	v_mfma_f32_16x16x32_bf16 v[92:95], v[136:139], v[190:193], v[92:95]
	v_mfma_f32_16x16x32_bf16 v[88:91], v[150:153], v[190:193], v[88:91]
	v_mfma_f32_16x16x32_bf16 v[76:79], v[136:139], v[198:201], v[76:79]
	v_mfma_f32_16x16x32_bf16 v[72:75], v[150:153], v[198:201], v[72:75]
	v_mfma_f32_16x16x32_bf16 v[124:127], v[146:149], v[178:181], v[124:127]
	v_mfma_f32_16x16x32_bf16 v[120:123], v[154:157], v[178:181], v[120:123]
	v_mfma_f32_16x16x32_bf16 v[108:111], v[146:149], v[186:189], v[108:111]
	v_mfma_f32_16x16x32_bf16 v[104:107], v[154:157], v[186:189], v[104:107]
	v_mfma_f32_16x16x32_bf16 v[92:95], v[146:149], v[194:197], v[92:95]
	v_mfma_f32_16x16x32_bf16 v[88:91], v[154:157], v[194:197], v[88:91]
	v_mfma_f32_16x16x32_bf16 v[76:79], v[146:149], v[202:205], v[76:79]
	v_mfma_f32_16x16x32_bf16 v[72:75], v[154:157], v[202:205], v[72:75]
	v_mfma_f32_16x16x32_bf16 v[116:119], v[158:161], v[174:177], v[116:119]
	v_mfma_f32_16x16x32_bf16 v[112:115], v[166:169], v[174:177], v[112:115]
	v_mfma_f32_16x16x32_bf16 v[100:103], v[158:161], v[182:185], v[100:103]
	v_mfma_f32_16x16x32_bf16 v[96:99], v[166:169], v[182:185], v[96:99]
	v_mfma_f32_16x16x32_bf16 v[84:87], v[158:161], v[190:193], v[84:87]
	v_mfma_f32_16x16x32_bf16 v[80:83], v[166:169], v[190:193], v[80:83]
	v_mfma_f32_16x16x32_bf16 v[68:71], v[158:161], v[198:201], v[68:71]
	v_mfma_f32_16x16x32_bf16 v[64:67], v[166:169], v[198:201], v[64:67]
	v_mfma_f32_16x16x32_bf16 v[116:119], v[162:165], v[178:181], v[116:119]
	v_mfma_f32_16x16x32_bf16 v[112:115], v[170:173], v[178:181], v[112:115]
	v_mfma_f32_16x16x32_bf16 v[100:103], v[162:165], v[186:189], v[100:103]
	v_mfma_f32_16x16x32_bf16 v[96:99], v[170:173], v[186:189], v[96:99]
	v_mfma_f32_16x16x32_bf16 v[84:87], v[162:165], v[194:197], v[84:87]
	v_mfma_f32_16x16x32_bf16 v[80:83], v[170:173], v[194:197], v[80:83]
	v_mfma_f32_16x16x32_bf16 v[68:71], v[162:165], v[202:205], v[68:71]
	v_mfma_f32_16x16x32_bf16 v[64:67], v[170:173], v[202:205], v[64:67]
	s_setprio 0
	s_barrier
	s_add_i32 s28, s57, s33
	v_lshl_add_u64 v[206:207], v[206:207], 0, s[18:19]
	s_mov_b32 m0, s28
	ds_read_b128 v[174:177], v145 offset:49152
	ds_read_b128 v[178:181], v145 offset:50176
	ds_read_b128 v[182:185], v145 offset:51200
	ds_read_b128 v[186:189], v145 offset:52224
	ds_read_b128 v[190:193], v145 offset:53248
	ds_read_b128 v[194:197], v145 offset:54272
	ds_read_b128 v[198:201], v145 offset:55296
	ds_read_b128 v[202:205], v145 offset:56320
	global_load_lds_dwordx4 v[206:207], off
	s_add_i32 m0, s28, 0x2000
	s_add_u32 s26, s26, 0x40080
	v_lshl_add_u64 v[206:207], v[208:209], 0, s[18:19]
	s_addc_u32 s27, s27, 0
	s_add_i32 s28, s58, s33
	global_load_lds_dwordx4 v[206:207], off
	v_lshl_add_u64 v[206:207], s[26:27], 0, v[130:131]
	s_mov_b32 m0, s28
	s_nop 0
	global_load_lds_dwordx4 v[206:207], off
	v_lshl_add_u64 v[206:207], s[26:27], 0, v[128:129]
	s_add_i32 m0, s28, 0x2000
	s_nop 0
	global_load_lds_dwordx4 v[206:207], off
	v_lshl_add_u64 v[206:207], v[210:211], 0, s[18:19]
	s_mov_b32 m0, s39
	s_nop 0
	global_load_lds_dwordx4 v[206:207], off
	v_lshl_add_u64 v[206:207], v[212:213], 0, s[18:19]
	s_mov_b32 m0, s40
	s_nop 0
	global_load_lds_dwordx4 v[206:207], off
	s_waitcnt vmcnt(8)
	s_waitcnt lgkmcnt(0)
	s_barrier
	s_setprio 1
	s_waitcnt lgkmcnt(0)
	v_mfma_f32_16x16x32_bf16 v[60:63], v[136:139], v[174:177], v[60:63]
	v_mfma_f32_16x16x32_bf16 v[56:59], v[150:153], v[174:177], v[56:59]
	v_mfma_f32_16x16x32_bf16 v[44:47], v[136:139], v[182:185], v[44:47]
	v_mfma_f32_16x16x32_bf16 v[40:43], v[150:153], v[182:185], v[40:43]
	v_mfma_f32_16x16x32_bf16 v[28:31], v[136:139], v[190:193], v[28:31]
	v_mfma_f32_16x16x32_bf16 v[24:27], v[150:153], v[190:193], v[24:27]
	v_mfma_f32_16x16x32_bf16 v[12:15], v[136:139], v[198:201], v[12:15]
	v_mfma_f32_16x16x32_bf16 v[8:11], v[150:153], v[198:201], v[8:11]
	v_mfma_f32_16x16x32_bf16 v[60:63], v[146:149], v[178:181], v[60:63]
	v_mfma_f32_16x16x32_bf16 v[56:59], v[154:157], v[178:181], v[56:59]
	v_mfma_f32_16x16x32_bf16 v[44:47], v[146:149], v[186:189], v[44:47]
	v_mfma_f32_16x16x32_bf16 v[40:43], v[154:157], v[186:189], v[40:43]
	v_mfma_f32_16x16x32_bf16 v[28:31], v[146:149], v[194:197], v[28:31]
	v_mfma_f32_16x16x32_bf16 v[24:27], v[154:157], v[194:197], v[24:27]
	v_mfma_f32_16x16x32_bf16 v[12:15], v[146:149], v[202:205], v[12:15]
	v_mfma_f32_16x16x32_bf16 v[8:11], v[154:157], v[202:205], v[8:11]
	v_mfma_f32_16x16x32_bf16 v[52:55], v[158:161], v[174:177], v[52:55]
	v_mfma_f32_16x16x32_bf16 v[48:51], v[166:169], v[174:177], v[48:51]
	v_mfma_f32_16x16x32_bf16 v[36:39], v[158:161], v[182:185], v[36:39]
	v_mfma_f32_16x16x32_bf16 v[32:35], v[166:169], v[182:185], v[32:35]
	v_mfma_f32_16x16x32_bf16 v[20:23], v[158:161], v[190:193], v[20:23]
	v_mfma_f32_16x16x32_bf16 v[16:19], v[166:169], v[190:193], v[16:19]
	v_mfma_f32_16x16x32_bf16 v[4:7], v[158:161], v[198:201], v[4:7]
	v_mfma_f32_16x16x32_bf16 v[0:3], v[166:169], v[198:201], v[0:3]
	v_mfma_f32_16x16x32_bf16 v[52:55], v[162:165], v[178:181], v[52:55]
	v_mfma_f32_16x16x32_bf16 v[48:51], v[170:173], v[178:181], v[48:51]
	v_mfma_f32_16x16x32_bf16 v[36:39], v[162:165], v[186:189], v[36:39]
	v_mfma_f32_16x16x32_bf16 v[32:35], v[170:173], v[186:189], v[32:35]
	v_mfma_f32_16x16x32_bf16 v[20:23], v[162:165], v[194:197], v[20:23]
	v_mfma_f32_16x16x32_bf16 v[16:19], v[170:173], v[194:197], v[16:19]
	v_mfma_f32_16x16x32_bf16 v[4:7], v[162:165], v[202:205], v[4:7]
	v_mfma_f32_16x16x32_bf16 v[0:3], v[170:173], v[202:205], v[0:3]
	s_setprio 0
	s_barrier
	s_add_i32 s56, s56, 2
	s_add_u32 s24, s24, 0x100
	s_addc_u32 s25, s25, 0
	s_add_u32 s50, s50, 0x100
	s_addc_u32 s51, s51, 0
	s_cmp_gt_u32 s56, 13
	s_cbranch_scc0 .LBB0_1058
	s_and_b64 vcc, exec, s[20:21]
	s_cbranch_vccz .LBB0_1061
	s_barrier

.LBB0_1130:
	s_cmp_lt_i32 s76, 1
	s_cselect_b64 s[26:27], -1, 0
	s_add_u32 s34, s34, 0x80080
	s_addc_u32 s35, s35, 0
	v_mov_b32_e32 v2, v0
	v_mov_b32_e32 v3, v0
	s_add_u32 s18, s2, 0x100
	v_mov_b32_e32 v1, v0
	v_mov_b32_e32 v84, 0
	v_mov_b64_e32 v[6:7], v[2:3]
	v_mov_b64_e32 v[10:11], v[2:3]
	v_mov_b64_e32 v[22:23], v[2:3]
	v_mov_b64_e32 v[26:27], v[2:3]
	v_mov_b64_e32 v[38:39], v[2:3]
	v_mov_b64_e32 v[42:43], v[2:3]
	v_mov_b64_e32 v[54:55], v[2:3]
	v_mov_b64_e32 v[58:59], v[2:3]
	v_mov_b64_e32 v[14:15], v[2:3]
	v_mov_b64_e32 v[18:19], v[2:3]
	v_mov_b64_e32 v[30:31], v[2:3]
	v_mov_b64_e32 v[34:35], v[2:3]
	v_mov_b64_e32 v[46:47], v[2:3]
	v_mov_b64_e32 v[50:51], v[2:3]
	v_mov_b64_e32 v[62:63], v[2:3]
	v_mov_b64_e32 v[66:67], v[2:3]
	v_mov_b64_e32 v[70:71], v[2:3]
	v_mov_b64_e32 v[74:75], v[2:3]
	v_mov_b64_e32 v[78:79], v[2:3]
	v_mov_b64_e32 v[82:83], v[2:3]
	v_mov_b64_e32 v[94:95], v[2:3]
	v_mov_b64_e32 v[98:99], v[2:3]
	v_mov_b64_e32 v[110:111], v[2:3]
	v_mov_b64_e32 v[114:115], v[2:3]
	s_addc_u32 s41, s3, 0
	s_mov_b32 s77, -2
	v_cndmask_b32_e64 v217, 0, 1, s[26:27]
	v_mov_b64_e32 v[4:5], v[0:1]
	v_mov_b64_e32 v[8:9], v[0:1]
	v_mov_b64_e32 v[20:21], v[0:1]
	v_mov_b64_e32 v[24:25], v[0:1]
	v_mov_b64_e32 v[36:37], v[0:1]
	v_mov_b64_e32 v[40:41], v[0:1]
	v_mov_b64_e32 v[52:53], v[0:1]
	v_mov_b64_e32 v[56:57], v[0:1]
	v_mov_b64_e32 v[12:13], v[0:1]
	v_mov_b64_e32 v[16:17], v[0:1]
	v_mov_b64_e32 v[28:29], v[0:1]
	v_mov_b64_e32 v[32:33], v[0:1]
	v_mov_b64_e32 v[44:45], v[0:1]
	v_mov_b64_e32 v[48:49], v[0:1]
	v_mov_b64_e32 v[60:61], v[0:1]
	v_mov_b64_e32 v[64:65], v[0:1]
	v_mov_b64_e32 v[68:69], v[0:1]
	v_mov_b64_e32 v[72:73], v[0:1]
	v_mov_b64_e32 v[76:77], v[0:1]
	v_mov_b64_e32 v[80:81], v[0:1]
	v_mov_b64_e32 v[92:93], v[0:1]
	v_mov_b64_e32 v[96:97], v[0:1]
	v_mov_b64_e32 v[108:109], v[0:1]
	v_mov_b64_e32 v[112:113], v[0:1]
	v_mov_b32_e32 v85, v84
	v_mov_b32_e32 v86, v84
	v_mov_b32_e32 v87, v84
	v_mov_b32_e32 v88, v84
	v_mov_b32_e32 v89, v84
	v_mov_b32_e32 v90, v84
	v_mov_b32_e32 v91, v84
	v_mov_b32_e32 v100, v84
	v_mov_b32_e32 v101, v84
	v_mov_b32_e32 v102, v84
	v_mov_b32_e32 v103, v84
	v_mov_b32_e32 v104, v84
	v_mov_b32_e32 v105, v84
	v_mov_b32_e32 v106, v84
	v_mov_b32_e32 v107, v84
	v_mov_b32_e32 v116, v84
	v_mov_b32_e32 v117, v84
	v_mov_b32_e32 v118, v84
	v_mov_b32_e32 v119, v84
	v_mov_b32_e32 v120, v84
	v_mov_b32_e32 v121, v84
	v_mov_b32_e32 v122, v84
	v_mov_b32_e32 v123, v84
	v_mov_b32_e32 v124, v84
	v_mov_b32_e32 v125, v84
	v_mov_b32_e32 v126, v84
	v_mov_b32_e32 v127, v84
	v_mov_b32_e32 v128, v84
	v_mov_b32_e32 v129, v84
	v_mov_b32_e32 v130, v84
	v_mov_b32_e32 v131, v84
	s_branch .LBB0_1132
	s_nop 0
	s_nop 0
	s_nop 0
	s_nop 0
	s_nop 0
.LBB0_1131:
	s_barrier
	s_add_i32 s77, s77, 2
	s_add_u32 s34, s34, 0x100
	s_addc_u32 s35, s35, 0
	s_add_u32 s18, s18, 0x100
	s_addc_u32 s41, s41, 0
	s_cmp_gt_u32 s77, 13
	s_cbranch_scc1 .LBB0_1140

.LBB0_1134:
	s_add_u32 s56, s34, 0xfff80080
	s_addc_u32 s57, s35, -1
	s_cmp_eq_u32 s77, 12
	s_cselect_b32 s59, s39, s57
	s_cselect_b32 s58, s38, s56
	s_cselect_b32 s57, s47, s41
	s_cselect_b32 s56, s46, s18
	s_barrier
	s_mov_b32 m0, s49
	v_lshl_add_u64 v[2:3], s[56:57], 0, v[198:199]
	s_add_u32 s78, s56, 0x80000
	ds_read_b128 v[188:191], v216 offset:16384
	ds_read_b128 v[192:195], v216 offset:17408
	ds_read_b128 v[180:183], v216 offset:18432
	ds_read_b128 v[184:187], v216 offset:19456
	ds_read_b128 v[172:175], v216 offset:20480
	ds_read_b128 v[176:179], v216 offset:21504
	ds_read_b128 v[164:167], v216 offset:22528
	ds_read_b128 v[168:171], v216 offset:23552
	global_load_lds_dwordx4 v[2:3], off
	v_lshl_add_u64 v[204:205], s[56:57], 0, v[196:197]
	s_mov_b32 m0, s50
	s_addc_u32 s79, s57, 0
	global_load_lds_dwordx4 v[204:205], off
	v_lshl_add_u64 v[206:207], s[78:79], 0, v[198:199]
	s_mov_b32 m0, s51
	v_lshl_add_u64 v[208:209], s[58:59], 0, v[196:197]
	global_load_lds_dwordx4 v[206:207], off
	v_lshl_add_u64 v[206:207], s[78:79], 0, v[196:197]
	s_mov_b32 m0, s60
	s_and_b64 vcc, exec, s[2:3]
	global_load_lds_dwordx4 v[206:207], off
	v_lshl_add_u64 v[206:207], s[58:59], 0, v[198:199]
	s_mov_b32 m0, s48
	s_nop 0
	global_load_lds_dwordx4 v[206:207], off
	s_mov_b32 m0, s61
	s_nop 0
	global_load_lds_dwordx4 v[208:209], off
	s_waitcnt vmcnt(8)
	s_waitcnt lgkmcnt(0)
	s_barrier
	s_setprio 1
	s_waitcnt lgkmcnt(0)
	v_mfma_f32_16x16x32_bf16 v[64:67], v[148:151], v[188:191], v[64:67]
	v_mfma_f32_16x16x32_bf16 v[60:63], v[156:159], v[188:191], v[60:63]
	v_mfma_f32_16x16x32_bf16 v[48:51], v[148:151], v[180:183], v[48:51]
	v_mfma_f32_16x16x32_bf16 v[44:47], v[156:159], v[180:183], v[44:47]
	v_mfma_f32_16x16x32_bf16 v[32:35], v[148:151], v[172:175], v[32:35]
	v_mfma_f32_16x16x32_bf16 v[28:31], v[156:159], v[172:175], v[28:31]
	v_mfma_f32_16x16x32_bf16 v[16:19], v[148:151], v[164:167], v[16:19]
	v_mfma_f32_16x16x32_bf16 v[12:15], v[156:159], v[164:167], v[12:15]
	v_mfma_f32_16x16x32_bf16 v[64:67], v[152:155], v[192:195], v[64:67]
	v_mfma_f32_16x16x32_bf16 v[60:63], v[160:163], v[192:195], v[60:63]
	v_mfma_f32_16x16x32_bf16 v[48:51], v[152:155], v[184:187], v[48:51]
	v_mfma_f32_16x16x32_bf16 v[44:47], v[160:163], v[184:187], v[44:47]
	v_mfma_f32_16x16x32_bf16 v[32:35], v[152:155], v[176:179], v[32:35]
	v_mfma_f32_16x16x32_bf16 v[28:31], v[160:163], v[176:179], v[28:31]
	v_mfma_f32_16x16x32_bf16 v[16:19], v[152:155], v[168:171], v[16:19]
	v_mfma_f32_16x16x32_bf16 v[12:15], v[160:163], v[168:171], v[12:15]
	v_mfma_f32_16x16x32_bf16 v[56:59], v[132:135], v[188:191], v[56:59]
	v_mfma_f32_16x16x32_bf16 v[52:55], v[140:143], v[188:191], v[52:55]
	v_mfma_f32_16x16x32_bf16 v[40:43], v[132:135], v[180:183], v[40:43]
	v_mfma_f32_16x16x32_bf16 v[36:39], v[140:143], v[180:183], v[36:39]
	v_mfma_f32_16x16x32_bf16 v[24:27], v[132:135], v[172:175], v[24:27]
	v_mfma_f32_16x16x32_bf16 v[20:23], v[140:143], v[172:175], v[20:23]
	v_mfma_f32_16x16x32_bf16 v[8:11], v[132:135], v[164:167], v[8:11]
	v_mfma_f32_16x16x32_bf16 v[4:7], v[140:143], v[164:167], v[4:7]
	v_mfma_f32_16x16x32_bf16 v[56:59], v[136:139], v[192:195], v[56:59]
	v_mfma_f32_16x16x32_bf16 v[52:55], v[144:147], v[192:195], v[52:55]
	v_mfma_f32_16x16x32_bf16 v[40:43], v[136:139], v[184:187], v[40:43]
	v_mfma_f32_16x16x32_bf16 v[36:39], v[144:147], v[184:187], v[36:39]
	v_mfma_f32_16x16x32_bf16 v[24:27], v[136:139], v[176:179], v[24:27]
	v_mfma_f32_16x16x32_bf16 v[20:23], v[144:147], v[176:179], v[20:23]
	v_mfma_f32_16x16x32_bf16 v[8:11], v[136:139], v[168:171], v[8:11]
	v_mfma_f32_16x16x32_bf16 v[4:7], v[144:147], v[168:171], v[4:7]
	s_setprio 0

.LBB0_1138:
	s_barrier
	s_mov_b32 m0, s66
	v_lshl_add_u64 v[2:3], v[2:3], 0, s[16:17]
	s_add_u32 s56, s56, 0x80080
	ds_read_b128 v[188:191], v216 offset:49152
	ds_read_b128 v[192:195], v216 offset:50176
	ds_read_b128 v[180:183], v216 offset:51200
	ds_read_b128 v[184:187], v216 offset:52224
	ds_read_b128 v[172:175], v216 offset:53248
	ds_read_b128 v[176:179], v216 offset:54272
	ds_read_b128 v[164:167], v216 offset:55296
	ds_read_b128 v[168:171], v216 offset:56320
	global_load_lds_dwordx4 v[2:3], off
	v_lshl_add_u64 v[2:3], v[204:205], 0, s[16:17]
	s_mov_b32 m0, s67
	s_addc_u32 s57, s57, 0
	global_load_lds_dwordx4 v[2:3], off
	v_lshl_add_u64 v[2:3], s[56:57], 0, v[198:199]
	s_mov_b32 m0, s70
	s_and_b64 vcc, exec, s[2:3]
	global_load_lds_dwordx4 v[2:3], off
	v_lshl_add_u64 v[2:3], s[56:57], 0, v[196:197]
	s_mov_b32 m0, s71
	s_nop 0
	global_load_lds_dwordx4 v[2:3], off
	v_lshl_add_u64 v[2:3], v[206:207], 0, s[16:17]
	s_mov_b32 m0, s68
	s_nop 0
	global_load_lds_dwordx4 v[2:3], off
	v_lshl_add_u64 v[2:3], v[208:209], 0, s[16:17]
	s_mov_b32 m0, s69
	s_nop 0
	global_load_lds_dwordx4 v[2:3], off
	s_waitcnt vmcnt(8)
	s_waitcnt lgkmcnt(0)
	s_barrier
	s_setprio 1
	s_waitcnt lgkmcnt(0)
	v_mfma_f32_16x16x32_bf16 v[64:67], v[148:151], v[188:191], v[64:67]
	v_mfma_f32_16x16x32_bf16 v[60:63], v[156:159], v[188:191], v[60:63]
	v_mfma_f32_16x16x32_bf16 v[48:51], v[148:151], v[180:183], v[48:51]
	v_mfma_f32_16x16x32_bf16 v[44:47], v[156:159], v[180:183], v[44:47]
	v_mfma_f32_16x16x32_bf16 v[32:35], v[148:151], v[172:175], v[32:35]
	v_mfma_f32_16x16x32_bf16 v[28:31], v[156:159], v[172:175], v[28:31]
	v_mfma_f32_16x16x32_bf16 v[16:19], v[148:151], v[164:167], v[16:19]
	v_mfma_f32_16x16x32_bf16 v[12:15], v[156:159], v[164:167], v[12:15]
	v_mfma_f32_16x16x32_bf16 v[64:67], v[152:155], v[192:195], v[64:67]
	v_mfma_f32_16x16x32_bf16 v[60:63], v[160:163], v[192:195], v[60:63]
	v_mfma_f32_16x16x32_bf16 v[48:51], v[152:155], v[184:187], v[48:51]
	v_mfma_f32_16x16x32_bf16 v[44:47], v[160:163], v[184:187], v[44:47]
	v_mfma_f32_16x16x32_bf16 v[32:35], v[152:155], v[176:179], v[32:35]
	v_mfma_f32_16x16x32_bf16 v[28:31], v[160:163], v[176:179], v[28:31]
	v_mfma_f32_16x16x32_bf16 v[16:19], v[152:155], v[168:171], v[16:19]
	v_mfma_f32_16x16x32_bf16 v[12:15], v[160:163], v[168:171], v[12:15]
	v_mfma_f32_16x16x32_bf16 v[56:59], v[132:135], v[188:191], v[56:59]
	v_mfma_f32_16x16x32_bf16 v[52:55], v[140:143], v[188:191], v[52:55]
	v_mfma_f32_16x16x32_bf16 v[40:43], v[132:135], v[180:183], v[40:43]
	v_mfma_f32_16x16x32_bf16 v[36:39], v[140:143], v[180:183], v[36:39]
	v_mfma_f32_16x16x32_bf16 v[24:27], v[132:135], v[172:175], v[24:27]
	v_mfma_f32_16x16x32_bf16 v[20:23], v[140:143], v[172:175], v[20:23]
	v_mfma_f32_16x16x32_bf16 v[8:11], v[132:135], v[164:167], v[8:11]
	v_mfma_f32_16x16x32_bf16 v[2:5], v[140:143], v[164:167], v[4:7]
	v_mfma_f32_16x16x32_bf16 v[56:59], v[136:139], v[192:195], v[56:59]
	v_mfma_f32_16x16x32_bf16 v[52:55], v[144:147], v[192:195], v[52:55]
	v_mfma_f32_16x16x32_bf16 v[40:43], v[136:139], v[184:187], v[40:43]
	v_mfma_f32_16x16x32_bf16 v[36:39], v[144:147], v[184:187], v[36:39]
	v_mfma_f32_16x16x32_bf16 v[24:27], v[136:139], v[176:179], v[24:27]
	v_mfma_f32_16x16x32_bf16 v[20:23], v[144:147], v[176:179], v[20:23]
	v_mfma_f32_16x16x32_bf16 v[8:11], v[136:139], v[168:171], v[8:11]
	v_mfma_f32_16x16x32_bf16 v[4:7], v[144:147], v[168:171], v[2:5]
	s_setprio 0
	s_branch .LBB0_1131
.Lq5_entry:
	v_mov_b32_e32 v4, 0
	v_mov_b32_e32 v5, 0
	v_mov_b32_e32 v6, 0
	v_mov_b32_e32 v7, 0
	v_mov_b32_e32 v8, 0
	v_mov_b32_e32 v9, 0
	v_mov_b32_e32 v10, 0
	v_mov_b32_e32 v11, 0
	v_mov_b32_e32 v12, 0
	v_mov_b32_e32 v13, 0
	v_mov_b32_e32 v14, 0
	v_mov_b32_e32 v15, 0
	v_mov_b32_e32 v16, 0
	v_mov_b32_e32 v17, 0
	v_mov_b32_e32 v18, 0
	v_mov_b32_e32 v19, 0
	v_mov_b32_e32 v20, 0
	v_mov_b32_e32 v21, 0
	v_mov_b32_e32 v22, 0
	v_mov_b32_e32 v23, 0
	v_mov_b32_e32 v24, 0
	v_mov_b32_e32 v25, 0
	v_mov_b32_e32 v26, 0
	v_mov_b32_e32 v27, 0
	v_mov_b32_e32 v28, 0
	v_mov_b32_e32 v29, 0
	v_mov_b32_e32 v30, 0
	v_mov_b32_e32 v31, 0
	v_mov_b32_e32 v32, 0
	v_mov_b32_e32 v33, 0
	v_mov_b32_e32 v34, 0
	v_mov_b32_e32 v35, 0
	v_mov_b32_e32 v36, 0
	v_mov_b32_e32 v37, 0
	v_mov_b32_e32 v38, 0
	v_mov_b32_e32 v39, 0
	v_mov_b32_e32 v40, 0
	v_mov_b32_e32 v41, 0
	v_mov_b32_e32 v42, 0
	v_mov_b32_e32 v43, 0
	v_mov_b32_e32 v44, 0
	v_mov_b32_e32 v45, 0
	v_mov_b32_e32 v46, 0
	v_mov_b32_e32 v47, 0
	v_mov_b32_e32 v48, 0
	v_mov_b32_e32 v49, 0
	v_mov_b32_e32 v50, 0
	v_mov_b32_e32 v51, 0
	v_cmp_ne_u32_e64 s[2:3], 1, v217
	s_andn2_b64 vcc, exec, s[26:27]
	s_add_u32 s56, s34, 0xfff80080
	s_addc_u32 s57, s35, -1
	s_cmp_eq_u32 s77, 12
	s_cselect_b32 s59, s39, s57
	s_cselect_b32 s58, s38, s56
	s_cselect_b32 s57, s47, s41
	s_cselect_b32 s56, s46, s18
	s_mov_b32 m0, s51
	v_lshl_add_u64 v[2:3], s[56:57], 0, v[198:199]
	s_add_u32 s78, s56, 0x80000
	global_load_lds_dwordx4 v[2:3], off
	v_lshl_add_u64 v[204:205], s[56:57], 0, v[196:197]
	s_mov_b32 m0, s60
	s_addc_u32 s79, s57, 0
	global_load_lds_dwordx4 v[204:205], off
	v_lshl_add_u64 v[206:207], s[78:79], 0, v[198:199]
	s_mov_b32 m0, s66
	v_lshl_add_u64 v[208:209], s[58:59], 0, v[196:197]
	v_lshl_add_u64 v[206:207], s[78:79], 0, v[196:197]
	s_mov_b32 m0, s67
	s_and_b64 vcc, exec, s[2:3]
	v_lshl_add_u64 v[206:207], s[58:59], 0, v[198:199]
	s_mov_b32 m0, s62
	s_nop 0
	global_load_lds_dwordx4 v[206:207], off
	s_mov_b32 m0, s63
	s_nop 0
	global_load_lds_dwordx4 v[208:209], off
	s_and_b64 vcc, exec, s[2:3]
	s_mov_b32 m0, s70
	v_lshl_add_u64 v[2:3], v[2:3], 0, s[16:17]
	s_add_u32 s56, s56, 0x80080
	global_load_lds_dwordx4 v[2:3], off
	v_lshl_add_u64 v[2:3], v[204:205], 0, s[16:17]
	s_mov_b32 m0, s71
	s_addc_u32 s57, s57, 0
	global_load_lds_dwordx4 v[2:3], off
	v_lshl_add_u64 v[2:3], s[56:57], 0, v[198:199]
	s_add_i32 m0, s48, 0x20000
	s_and_b64 vcc, exec, s[2:3]
	v_lshl_add_u64 v[2:3], s[56:57], 0, v[196:197]
	s_add_i32 m0, s48, 0x22000
	s_nop 0
	v_lshl_add_u64 v[2:3], v[206:207], 0, s[16:17]
	s_add_i32 m0, s48, 0xc000
	s_nop 0
	global_load_lds_dwordx4 v[2:3], off
	v_lshl_add_u64 v[2:3], v[208:209], 0, s[16:17]
	s_add_i32 m0, s48, 0xe000
	s_nop 0
	global_load_lds_dwordx4 v[2:3], off
	s_add_u32 s34, s34, 0x100
	s_addc_u32 s35, s35, 0
	s_add_u32 s18, s18, 0x100
	s_addc_u32 s41, s41, 0
	s_branch .Lq5_top
	s_nop 0
	s_nop 0
	s_nop 0
	s_nop 0
	s_nop 0
	s_nop 0

.LBB0_1285:
	s_add_u32 s40, s38, 0xfff80080
	s_addc_u32 s41, s39, -1
	s_cmp_eq_u32 s84, 28
	s_cselect_b32 s47, s29, s41
	s_cselect_b32 s46, s28, s40
	s_cselect_b32 s41, s37, s27
	s_cselect_b32 s40, s36, s16
	s_barrier
	s_mov_b32 m0, s45
	v_lshl_add_u64 v[2:3], s[40:41], 0, v[230:231]
	s_add_u32 s86, s40, 0x80000
	ds_read_b128 v[156:159], v249 offset:16384
	ds_read_b128 v[160:163], v249 offset:17408
	ds_read_b128 v[148:151], v249 offset:18432
	ds_read_b128 v[152:155], v249 offset:19456
	ds_read_b128 v[132:135], v249 offset:20480
	ds_read_b128 v[136:139], v249 offset:21504
	ds_read_b128 v[112:115], v249 offset:22528
	ds_read_b128 v[120:123], v249 offset:23552
	global_load_lds_dwordx4 v[2:3], off
	v_lshl_add_u64 v[236:237], s[40:41], 0, v[228:229]
	s_mov_b32 m0, s48
	s_addc_u32 s87, s41, 0
	global_load_lds_dwordx4 v[236:237], off
	v_lshl_add_u64 v[196:197], s[86:87], 0, v[230:231]
	s_mov_b32 m0, s49
	v_lshl_add_u64 v[238:239], s[46:47], 0, v[230:231]
	global_load_lds_dwordx4 v[196:197], off
	v_lshl_add_u64 v[196:197], s[86:87], 0, v[228:229]
	s_mov_b32 m0, s50
	v_lshl_add_u64 v[240:241], s[46:47], 0, v[228:229]
	global_load_lds_dwordx4 v[196:197], off
	s_mov_b32 m0, s44
	s_and_b64 vcc, exec, s[4:5]
	global_load_lds_dwordx4 v[238:239], off
	s_mov_b32 m0, s51
	s_nop 0
	global_load_lds_dwordx4 v[240:241], off
	s_waitcnt vmcnt(8)
	s_waitcnt lgkmcnt(0)
	s_barrier
	s_setprio 1
	s_waitcnt lgkmcnt(0)
	v_mfma_f32_16x16x32_bf16 v[64:67], v[180:183], v[156:159], v[64:67]
	v_mfma_f32_16x16x32_bf16 v[60:63], v[188:191], v[156:159], v[60:63]
	v_mfma_f32_16x16x32_bf16 v[48:51], v[180:183], v[148:151], v[48:51]
	v_mfma_f32_16x16x32_bf16 v[44:47], v[188:191], v[148:151], v[44:47]
	v_mfma_f32_16x16x32_bf16 v[32:35], v[180:183], v[132:135], v[32:35]
	v_mfma_f32_16x16x32_bf16 v[28:31], v[188:191], v[132:135], v[28:31]
	v_mfma_f32_16x16x32_bf16 v[16:19], v[180:183], v[112:115], v[16:19]
	v_mfma_f32_16x16x32_bf16 v[12:15], v[188:191], v[112:115], v[12:15]
	v_mfma_f32_16x16x32_bf16 v[64:67], v[184:187], v[160:163], v[64:67]
	v_mfma_f32_16x16x32_bf16 v[60:63], v[192:195], v[160:163], v[60:63]
	v_mfma_f32_16x16x32_bf16 v[48:51], v[184:187], v[152:155], v[48:51]
	v_mfma_f32_16x16x32_bf16 v[44:47], v[192:195], v[152:155], v[44:47]
	v_mfma_f32_16x16x32_bf16 v[32:35], v[184:187], v[136:139], v[32:35]
	v_mfma_f32_16x16x32_bf16 v[28:31], v[192:195], v[136:139], v[28:31]
	v_mfma_f32_16x16x32_bf16 v[16:19], v[184:187], v[120:123], v[16:19]
	v_mfma_f32_16x16x32_bf16 v[12:15], v[192:195], v[120:123], v[12:15]
	v_mfma_f32_16x16x32_bf16 v[56:59], v[164:167], v[156:159], v[56:59]
	v_mfma_f32_16x16x32_bf16 v[52:55], v[172:175], v[156:159], v[52:55]
	v_mfma_f32_16x16x32_bf16 v[40:43], v[164:167], v[148:151], v[40:43]
	v_mfma_f32_16x16x32_bf16 v[36:39], v[172:175], v[148:151], v[36:39]
	v_mfma_f32_16x16x32_bf16 v[24:27], v[164:167], v[132:135], v[24:27]
	v_mfma_f32_16x16x32_bf16 v[20:23], v[172:175], v[132:135], v[20:23]
	v_mfma_f32_16x16x32_bf16 v[8:11], v[164:167], v[112:115], v[8:11]
	v_mfma_f32_16x16x32_bf16 v[4:7], v[172:175], v[112:115], v[4:7]
	v_mfma_f32_16x16x32_bf16 v[56:59], v[168:171], v[160:163], v[56:59]
	v_mfma_f32_16x16x32_bf16 v[52:55], v[176:179], v[160:163], v[52:55]
	v_mfma_f32_16x16x32_bf16 v[40:43], v[168:171], v[152:155], v[40:43]
	v_mfma_f32_16x16x32_bf16 v[36:39], v[176:179], v[152:155], v[36:39]
	v_mfma_f32_16x16x32_bf16 v[24:27], v[168:171], v[136:139], v[24:27]
	v_mfma_f32_16x16x32_bf16 v[20:23], v[176:179], v[136:139], v[20:23]
	v_mfma_f32_16x16x32_bf16 v[8:11], v[168:171], v[120:123], v[8:11]
	v_mfma_f32_16x16x32_bf16 v[4:7], v[176:179], v[120:123], v[4:7]
	s_setprio 0

.LBB0_1289:
	s_barrier
	s_mov_b32 m0, s61
	v_lshl_add_u64 v[2:3], v[2:3], 0, s[14:15]
	s_add_u32 s40, s40, 0x80080
	ds_read_b128 v[96:99], v249 offset:49152
	ds_read_b128 v[100:103], v249 offset:50176
	ds_read_b128 v[84:87], v249 offset:51200
	ds_read_b128 v[92:95], v249 offset:52224
	ds_read_b128 v[76:79], v249 offset:53248
	ds_read_b128 v[80:83], v249 offset:54272
	ds_read_b128 v[68:71], v249 offset:55296
	ds_read_b128 v[72:75], v249 offset:56320
	global_load_lds_dwordx4 v[2:3], off
	v_lshl_add_u64 v[2:3], v[236:237], 0, s[14:15]
	s_mov_b32 m0, s62
	s_addc_u32 s41, s41, 0
	global_load_lds_dwordx4 v[2:3], off
	v_lshl_add_u64 v[2:3], s[40:41], 0, v[230:231]
	s_mov_b32 m0, s65
	s_and_b64 vcc, exec, s[4:5]
	global_load_lds_dwordx4 v[2:3], off
	v_lshl_add_u64 v[2:3], s[40:41], 0, v[228:229]
	s_mov_b32 m0, s66
	s_nop 0
	global_load_lds_dwordx4 v[2:3], off
	v_lshl_add_u64 v[2:3], v[238:239], 0, s[14:15]
	s_mov_b32 m0, s63
	s_nop 0
	global_load_lds_dwordx4 v[2:3], off
	v_lshl_add_u64 v[2:3], v[240:241], 0, s[14:15]
	s_mov_b32 m0, s64
	s_nop 0
	global_load_lds_dwordx4 v[2:3], off
	s_waitcnt vmcnt(8)
	s_waitcnt lgkmcnt(0)
	s_barrier
	s_setprio 1
	s_waitcnt lgkmcnt(0)
	v_mfma_f32_16x16x32_bf16 v[64:67], v[180:183], v[96:99], v[64:67]
	v_mfma_f32_16x16x32_bf16 v[60:63], v[188:191], v[96:99], v[60:63]
	v_mfma_f32_16x16x32_bf16 v[48:51], v[180:183], v[84:87], v[48:51]
	v_mfma_f32_16x16x32_bf16 v[44:47], v[188:191], v[84:87], v[44:47]
	v_mfma_f32_16x16x32_bf16 v[32:35], v[180:183], v[76:79], v[32:35]
	v_mfma_f32_16x16x32_bf16 v[28:31], v[188:191], v[76:79], v[28:31]
	v_mfma_f32_16x16x32_bf16 v[16:19], v[180:183], v[68:71], v[16:19]
	v_mfma_f32_16x16x32_bf16 v[12:15], v[188:191], v[68:71], v[12:15]
	v_mfma_f32_16x16x32_bf16 v[64:67], v[184:187], v[100:103], v[64:67]
	v_mfma_f32_16x16x32_bf16 v[60:63], v[192:195], v[100:103], v[60:63]
	v_mfma_f32_16x16x32_bf16 v[48:51], v[184:187], v[92:95], v[48:51]
	v_mfma_f32_16x16x32_bf16 v[44:47], v[192:195], v[92:95], v[44:47]
	v_mfma_f32_16x16x32_bf16 v[32:35], v[184:187], v[80:83], v[32:35]
	v_mfma_f32_16x16x32_bf16 v[28:31], v[192:195], v[80:83], v[28:31]
	v_mfma_f32_16x16x32_bf16 v[16:19], v[184:187], v[72:75], v[16:19]
	v_mfma_f32_16x16x32_bf16 v[12:15], v[192:195], v[72:75], v[12:15]
	v_mfma_f32_16x16x32_bf16 v[56:59], v[164:167], v[96:99], v[56:59]
	v_mfma_f32_16x16x32_bf16 v[52:55], v[172:175], v[96:99], v[52:55]
	v_mfma_f32_16x16x32_bf16 v[40:43], v[164:167], v[84:87], v[40:43]
	v_mfma_f32_16x16x32_bf16 v[36:39], v[172:175], v[84:87], v[36:39]
	v_mfma_f32_16x16x32_bf16 v[24:27], v[164:167], v[76:79], v[24:27]
	v_mfma_f32_16x16x32_bf16 v[20:23], v[172:175], v[76:79], v[20:23]
	v_mfma_f32_16x16x32_bf16 v[8:11], v[164:167], v[68:71], v[8:11]
	v_mfma_f32_16x16x32_bf16 v[2:5], v[172:175], v[68:71], v[4:7]
	v_mfma_f32_16x16x32_bf16 v[56:59], v[168:171], v[100:103], v[56:59]
	v_mfma_f32_16x16x32_bf16 v[52:55], v[176:179], v[100:103], v[52:55]
	v_mfma_f32_16x16x32_bf16 v[40:43], v[168:171], v[92:95], v[40:43]
	v_mfma_f32_16x16x32_bf16 v[36:39], v[176:179], v[92:95], v[36:39]
	v_mfma_f32_16x16x32_bf16 v[24:27], v[168:171], v[80:83], v[24:27]
	v_mfma_f32_16x16x32_bf16 v[20:23], v[176:179], v[80:83], v[20:23]
	v_mfma_f32_16x16x32_bf16 v[8:11], v[168:171], v[72:75], v[8:11]
	v_mfma_f32_16x16x32_bf16 v[4:7], v[176:179], v[72:75], v[2:5]
	s_setprio 0
	s_branch .LBB0_1282
.Lq6_entry:
	v_mov_b32_e32 v4, 0
	v_mov_b32_e32 v5, 0
	v_mov_b32_e32 v6, 0
	v_mov_b32_e32 v7, 0
	v_mov_b32_e32 v8, 0
	v_mov_b32_e32 v9, 0
	v_mov_b32_e32 v10, 0
	v_mov_b32_e32 v11, 0
	v_mov_b32_e32 v12, 0
	v_mov_b32_e32 v13, 0
	v_mov_b32_e32 v14, 0
	v_mov_b32_e32 v15, 0
	v_mov_b32_e32 v16, 0
	v_mov_b32_e32 v17, 0
	v_mov_b32_e32 v18, 0
	v_mov_b32_e32 v19, 0
	v_mov_b32_e32 v20, 0
	v_mov_b32_e32 v21, 0
	v_mov_b32_e32 v22, 0
	v_mov_b32_e32 v23, 0
	v_mov_b32_e32 v24, 0
	v_mov_b32_e32 v25, 0
	v_mov_b32_e32 v26, 0
	v_mov_b32_e32 v27, 0
	v_mov_b32_e32 v28, 0
	v_mov_b32_e32 v29, 0
	v_mov_b32_e32 v30, 0
	v_mov_b32_e32 v31, 0
	v_mov_b32_e32 v32, 0
	v_mov_b32_e32 v33, 0
	v_mov_b32_e32 v34, 0
	v_mov_b32_e32 v35, 0
	v_mov_b32_e32 v36, 0
	v_mov_b32_e32 v37, 0
	v_mov_b32_e32 v38, 0
	v_mov_b32_e32 v39, 0
	v_mov_b32_e32 v40, 0
	v_mov_b32_e32 v41, 0
	v_mov_b32_e32 v42, 0
	v_mov_b32_e32 v43, 0
	v_mov_b32_e32 v44, 0
	v_mov_b32_e32 v45, 0
	v_mov_b32_e32 v46, 0
	v_mov_b32_e32 v47, 0
	v_mov_b32_e32 v48, 0
	v_mov_b32_e32 v49, 0
	v_mov_b32_e32 v50, 0
	v_mov_b32_e32 v51, 0
	v_cmp_ne_u32_e64 s[4:5], 1, v251
	s_andn2_b64 vcc, exec, s[34:35]
	s_add_u32 s40, s38, 0xfff80080
	s_addc_u32 s41, s39, -1
	s_cmp_eq_u32 s84, 28
	s_cselect_b32 s47, s29, s41
	s_cselect_b32 s46, s28, s40
	s_cselect_b32 s41, s37, s27
	s_cselect_b32 s40, s36, s16
	s_mov_b32 m0, s49
	v_lshl_add_u64 v[2:3], s[40:41], 0, v[230:231]
	s_add_u32 s86, s40, 0x80000
	global_load_lds_dwordx4 v[2:3], off
	v_lshl_add_u64 v[236:237], s[40:41], 0, v[228:229]
	s_mov_b32 m0, s50
	s_addc_u32 s87, s41, 0
	global_load_lds_dwordx4 v[236:237], off
	v_lshl_add_u64 v[54:55], s[86:87], 0, v[230:231]
	s_mov_b32 m0, s61
	v_lshl_add_u64 v[238:239], s[46:47], 0, v[230:231]
	v_lshl_add_u64 v[54:55], s[86:87], 0, v[228:229]
	s_mov_b32 m0, s62
	v_lshl_add_u64 v[240:241], s[46:47], 0, v[228:229]
	s_mov_b32 m0, s56
	s_and_b64 vcc, exec, s[4:5]
	global_load_lds_dwordx4 v[238:239], off
	s_mov_b32 m0, s57
	s_nop 0
	global_load_lds_dwordx4 v[240:241], off
	s_and_b64 vcc, exec, s[4:5]
	s_mov_b32 m0, s65
	v_lshl_add_u64 v[2:3], v[2:3], 0, s[14:15]
	s_add_u32 s40, s40, 0x80080
	global_load_lds_dwordx4 v[2:3], off
	v_lshl_add_u64 v[2:3], v[236:237], 0, s[14:15]
	s_mov_b32 m0, s66
	s_addc_u32 s41, s41, 0
	global_load_lds_dwordx4 v[2:3], off
	v_lshl_add_u64 v[2:3], s[40:41], 0, v[230:231]
	s_add_i32 m0, s44, 0x20000
	s_and_b64 vcc, exec, s[4:5]
	v_lshl_add_u64 v[2:3], s[40:41], 0, v[228:229]
	s_add_i32 m0, s44, 0x22000
	s_nop 0
	v_lshl_add_u64 v[2:3], v[238:239], 0, s[14:15]
	s_add_i32 m0, s44, 0xc000
	s_nop 0
	global_load_lds_dwordx4 v[2:3], off
	v_lshl_add_u64 v[2:3], v[240:241], 0, s[14:15]
	s_add_i32 m0, s44, 0xe000
	s_nop 0
	global_load_lds_dwordx4 v[2:3], off
	s_add_u32 s38, s38, 0x100
	s_addc_u32 s39, s39, 0
	s_add_u32 s16, s16, 0x100
	s_addc_u32 s27, s27, 0
	s_branch .Lq6_top
	s_nop 0
	s_nop 0
	s_nop 0
	s_nop 0
	s_nop 0
	s_nop 0
	s_nop 0
	s_nop 0
	s_nop 0

.LBB0_1391:
	ds_read_b128 v[24:27], v234
	ds_read_b128 v[28:31], v234 offset:1024
	ds_read_b128 v[96:99], v234 offset:2048
	ds_read_b128 v[100:103], v234 offset:3072
	ds_read_b128 v[144:147], v235
	ds_read_b128 v[148:151], v235 offset:1024
	ds_read_b128 v[152:155], v235 offset:2048
	ds_read_b128 v[156:159], v235 offset:3072
	s_add_u32 s16, s14, 0xfff80080
	s_addc_u32 s17, s15, -1
	s_cmp_eq_u32 s22, 28
	s_cselect_b32 s19, s9, s17
	s_cselect_b32 s18, s13, s16
	s_cselect_b32 s17, s79, s21
	s_cselect_b32 s16, s78, s20
	v_lshl_add_u64 v[204:205], s[14:15], 0, v[192:193]
	s_add_i32 m0, s49, 0xc000
	ds_read_b128 v[160:163], v236
	ds_read_b128 v[164:167], v236 offset:1024
	ds_read_b128 v[168:171], v236 offset:2048
	ds_read_b128 v[172:175], v236 offset:3072
	ds_read_b128 v[176:179], v236 offset:4096
	ds_read_b128 v[180:183], v236 offset:5120
	ds_read_b128 v[196:199], v236 offset:6144
	ds_read_b128 v[200:203], v236 offset:7168
	global_load_lds_dwordx4 v[204:205], off
	v_lshl_add_u64 v[204:205], s[14:15], 0, v[194:195]
	s_add_i32 m0, s49, 0xe000
	s_nop 0
	global_load_lds_dwordx4 v[204:205], off
	s_waitcnt vmcnt(8)
	s_waitcnt lgkmcnt(0)
	s_barrier
	s_setprio 1
	s_waitcnt lgkmcnt(0)
	v_mfma_f32_16x16x32_bf16 v[140:143], v[24:27], v[160:163], v[140:143]
	v_mfma_f32_16x16x32_bf16 v[84:87], v[96:99], v[160:163], v[84:87]
	v_mfma_f32_16x16x32_bf16 v[116:119], v[24:27], v[168:171], v[116:119]
	v_mfma_f32_16x16x32_bf16 v[44:47], v[96:99], v[168:171], v[44:47]
	v_mfma_f32_16x16x32_bf16 v[108:111], v[24:27], v[176:179], v[108:111]
	v_mfma_f32_16x16x32_bf16 v[36:39], v[96:99], v[176:179], v[36:39]
	v_mfma_f32_16x16x32_bf16 v[136:139], v[24:27], v[196:199], v[136:139]
	v_mfma_f32_16x16x32_bf16 v[56:59], v[96:99], v[196:199], v[56:59]
	v_mfma_f32_16x16x32_bf16 v[140:143], v[28:31], v[164:167], v[140:143]
	v_mfma_f32_16x16x32_bf16 v[84:87], v[100:103], v[164:167], v[84:87]
	v_mfma_f32_16x16x32_bf16 v[116:119], v[28:31], v[172:175], v[116:119]
	v_mfma_f32_16x16x32_bf16 v[44:47], v[100:103], v[172:175], v[44:47]
	v_mfma_f32_16x16x32_bf16 v[108:111], v[28:31], v[180:183], v[108:111]
	v_mfma_f32_16x16x32_bf16 v[36:39], v[100:103], v[180:183], v[36:39]
	v_mfma_f32_16x16x32_bf16 v[136:139], v[28:31], v[200:203], v[136:139]
	v_mfma_f32_16x16x32_bf16 v[56:59], v[100:103], v[200:203], v[56:59]
	v_mfma_f32_16x16x32_bf16 v[128:131], v[144:147], v[160:163], v[128:131]
	v_mfma_f32_16x16x32_bf16 v[80:83], v[152:155], v[160:163], v[80:83]
	v_mfma_f32_16x16x32_bf16 v[112:115], v[144:147], v[168:171], v[112:115]
	v_mfma_f32_16x16x32_bf16 v[40:43], v[152:155], v[168:171], v[40:43]
	v_mfma_f32_16x16x32_bf16 v[104:107], v[144:147], v[176:179], v[104:107]
	v_mfma_f32_16x16x32_bf16 v[32:35], v[152:155], v[176:179], v[32:35]
	v_mfma_f32_16x16x32_bf16 v[132:135], v[144:147], v[196:199], v[132:135]
	v_mfma_f32_16x16x32_bf16 v[60:63], v[152:155], v[196:199], v[60:63]
	v_mfma_f32_16x16x32_bf16 v[128:131], v[148:151], v[164:167], v[128:131]
	v_mfma_f32_16x16x32_bf16 v[80:83], v[156:159], v[164:167], v[80:83]
	v_mfma_f32_16x16x32_bf16 v[112:115], v[148:151], v[172:175], v[112:115]
	v_mfma_f32_16x16x32_bf16 v[40:43], v[156:159], v[172:175], v[40:43]
	v_mfma_f32_16x16x32_bf16 v[104:107], v[148:151], v[180:183], v[104:107]
	v_mfma_f32_16x16x32_bf16 v[32:35], v[156:159], v[180:183], v[32:35]
	v_mfma_f32_16x16x32_bf16 v[132:135], v[148:151], v[200:203], v[132:135]
	v_mfma_f32_16x16x32_bf16 v[60:63], v[156:159], v[200:203], v[60:63]
	s_setprio 0
	s_barrier
	s_add_i32 s23, s45, s51
	v_lshl_add_u64 v[204:205], s[16:17], 0, v[188:189]
	s_mov_b32 m0, s23
	ds_read_b128 v[160:163], v236 offset:16384
	ds_read_b128 v[164:167], v236 offset:17408
	ds_read_b128 v[168:171], v236 offset:18432
	ds_read_b128 v[172:175], v236 offset:19456
	ds_read_b128 v[176:179], v236 offset:20480
	ds_read_b128 v[180:183], v236 offset:21504
	ds_read_b128 v[196:199], v236 offset:22528
	ds_read_b128 v[200:203], v236 offset:23552
	global_load_lds_dwordx4 v[204:205], off
	s_add_i32 m0, s23, 0x2000
	s_add_u32 s24, s16, 0x84000
	v_lshl_add_u64 v[206:207], s[16:17], 0, v[184:185]
	s_addc_u32 s25, s17, 0
	s_add_i32 s23, s48, s51
	global_load_lds_dwordx4 v[206:207], off
	v_lshl_add_u64 v[208:209], s[24:25], 0, v[188:189]
	s_mov_b32 m0, s23
	v_lshl_add_u64 v[210:211], s[18:19], 0, v[186:187]
	global_load_lds_dwordx4 v[208:209], off
	v_lshl_add_u64 v[208:209], s[24:25], 0, v[184:185]
	s_add_i32 m0, s23, 0x2000
	s_nop 0
	global_load_lds_dwordx4 v[208:209], off
	v_lshl_add_u64 v[208:209], s[18:19], 0, v[190:191]
	s_mov_b32 m0, s49
	s_nop 0
	global_load_lds_dwordx4 v[208:209], off
	s_mov_b32 m0, s50
	s_nop 0
	global_load_lds_dwordx4 v[210:211], off
	s_waitcnt vmcnt(8)
	s_waitcnt lgkmcnt(0)
	s_barrier
	s_setprio 1
	s_waitcnt lgkmcnt(0)
	v_mfma_f32_16x16x32_bf16 v[124:127], v[24:27], v[160:163], v[124:127]
	v_mfma_f32_16x16x32_bf16 v[52:55], v[96:99], v[160:163], v[52:55]
	v_mfma_f32_16x16x32_bf16 v[76:79], v[24:27], v[168:171], v[76:79]
	v_mfma_f32_16x16x32_bf16 v[12:15], v[96:99], v[168:171], v[12:15]
	v_mfma_f32_16x16x32_bf16 v[68:71], v[24:27], v[176:179], v[68:71]
	v_mfma_f32_16x16x32_bf16 v[4:7], v[96:99], v[176:179], v[4:7]
	v_mfma_f32_16x16x32_bf16 v[16:19], v[96:99], v[196:199], v[16:19]
	v_mfma_f32_16x16x32_bf16 v[124:127], v[28:31], v[164:167], v[124:127]
	v_mfma_f32_16x16x32_bf16 v[52:55], v[100:103], v[164:167], v[52:55]
	v_mfma_f32_16x16x32_bf16 v[76:79], v[28:31], v[172:175], v[76:79]
	v_mfma_f32_16x16x32_bf16 v[12:15], v[100:103], v[172:175], v[12:15]
	v_mfma_f32_16x16x32_bf16 v[68:71], v[28:31], v[180:183], v[68:71]
	v_mfma_f32_16x16x32_bf16 v[4:7], v[100:103], v[180:183], v[4:7]
	v_mfma_f32_16x16x32_bf16 v[24:27], v[24:27], v[196:199], v[88:91]
	v_mfma_f32_16x16x32_bf16 v[16:19], v[100:103], v[200:203], v[16:19]
	v_mfma_f32_16x16x32_bf16 v[24:27], v[28:31], v[200:203], v[24:27]
	v_mfma_f32_16x16x32_bf16 v[48:51], v[152:155], v[160:163], v[48:51]
	v_mfma_f32_16x16x32_bf16 v[72:75], v[144:147], v[168:171], v[72:75]
	v_mfma_f32_16x16x32_bf16 v[8:11], v[152:155], v[168:171], v[8:11]
	v_mfma_f32_16x16x32_bf16 v[64:67], v[144:147], v[176:179], v[64:67]
	v_mfma_f32_16x16x32_bf16 v[0:3], v[152:155], v[176:179], v[0:3]
	v_mfma_f32_16x16x32_bf16 v[88:91], v[144:147], v[196:199], v[92:95]
	v_mfma_f32_16x16x32_bf16 v[20:23], v[152:155], v[196:199], v[20:23]
	v_mfma_f32_16x16x32_bf16 v[28:31], v[144:147], v[160:163], v[120:123]
	v_mfma_f32_16x16x32_bf16 v[48:51], v[156:159], v[164:167], v[48:51]
	v_mfma_f32_16x16x32_bf16 v[72:75], v[148:151], v[172:175], v[72:75]
	v_mfma_f32_16x16x32_bf16 v[8:11], v[156:159], v[172:175], v[8:11]
	v_mfma_f32_16x16x32_bf16 v[64:67], v[148:151], v[180:183], v[64:67]
	v_mfma_f32_16x16x32_bf16 v[0:3], v[156:159], v[180:183], v[0:3]
	v_mfma_f32_16x16x32_bf16 v[92:95], v[148:151], v[200:203], v[88:91]
	v_mfma_f32_16x16x32_bf16 v[20:23], v[156:159], v[200:203], v[20:23]
	v_mfma_f32_16x16x32_bf16 v[28:31], v[148:151], v[164:167], v[28:31]
	s_setprio 0
	s_barrier
	s_add_i32 s23, 0, 0x18000
	s_add_i32 s24, 0, 0x1c000
	v_add_u32_e32 v120, s23, v222
	v_add_u32_e32 v156, s24, v222
	ds_read_b128 v[88:91], v120
	ds_read_b128 v[96:99], v120 offset:1024
	ds_read_b128 v[100:103], v120 offset:2048
	ds_read_b128 v[120:123], v120 offset:3072
	ds_read_b128 v[144:147], v156
	ds_read_b128 v[148:151], v156 offset:1024
	ds_read_b128 v[152:155], v156 offset:2048
	ds_read_b128 v[156:159], v156 offset:3072
	s_add_u32 s18, s18, 0x80000
	s_addc_u32 s19, s19, 0
	s_mov_b32 m0, s33
	v_lshl_add_u64 v[212:213], s[18:19], 0, v[190:191]
	ds_read_b128 v[160:163], v236 offset:32768
	ds_read_b128 v[164:167], v236 offset:33792
	ds_read_b128 v[168:171], v236 offset:34816
	ds_read_b128 v[172:175], v236 offset:35840
	ds_read_b128 v[176:179], v236 offset:36864
	ds_read_b128 v[180:183], v236 offset:37888
	ds_read_b128 v[196:199], v236 offset:38912
	ds_read_b128 v[200:203], v236 offset:39936
	global_load_lds_dwordx4 v[212:213], off
	v_lshl_add_u64 v[212:213], s[18:19], 0, v[186:187]
	s_mov_b32 m0, s30
	s_nop 0
	global_load_lds_dwordx4 v[212:213], off
	s_waitcnt vmcnt(8)
	s_waitcnt lgkmcnt(0)
	s_barrier
	s_setprio 1
	s_waitcnt lgkmcnt(0)
	v_mfma_f32_16x16x32_bf16 v[140:143], v[88:91], v[160:163], v[140:143]
	v_mfma_f32_16x16x32_bf16 v[84:87], v[100:103], v[160:163], v[84:87]
	v_mfma_f32_16x16x32_bf16 v[116:119], v[88:91], v[168:171], v[116:119]
	v_mfma_f32_16x16x32_bf16 v[44:47], v[100:103], v[168:171], v[44:47]
	v_mfma_f32_16x16x32_bf16 v[108:111], v[88:91], v[176:179], v[108:111]
	v_mfma_f32_16x16x32_bf16 v[36:39], v[100:103], v[176:179], v[36:39]
	v_mfma_f32_16x16x32_bf16 v[136:139], v[88:91], v[196:199], v[136:139]
	v_mfma_f32_16x16x32_bf16 v[56:59], v[100:103], v[196:199], v[56:59]
	v_mfma_f32_16x16x32_bf16 v[140:143], v[96:99], v[164:167], v[140:143]
	v_mfma_f32_16x16x32_bf16 v[84:87], v[120:123], v[164:167], v[84:87]
	v_mfma_f32_16x16x32_bf16 v[116:119], v[96:99], v[172:175], v[116:119]
	v_mfma_f32_16x16x32_bf16 v[44:47], v[120:123], v[172:175], v[44:47]
	v_mfma_f32_16x16x32_bf16 v[108:111], v[96:99], v[180:183], v[108:111]
	v_mfma_f32_16x16x32_bf16 v[36:39], v[120:123], v[180:183], v[36:39]
	v_mfma_f32_16x16x32_bf16 v[136:139], v[96:99], v[200:203], v[136:139]
	v_mfma_f32_16x16x32_bf16 v[56:59], v[120:123], v[200:203], v[56:59]
	v_mfma_f32_16x16x32_bf16 v[128:131], v[144:147], v[160:163], v[128:131]
	v_mfma_f32_16x16x32_bf16 v[80:83], v[152:155], v[160:163], v[80:83]
	v_mfma_f32_16x16x32_bf16 v[112:115], v[144:147], v[168:171], v[112:115]
	v_mfma_f32_16x16x32_bf16 v[40:43], v[152:155], v[168:171], v[40:43]
	v_mfma_f32_16x16x32_bf16 v[104:107], v[144:147], v[176:179], v[104:107]
	v_mfma_f32_16x16x32_bf16 v[32:35], v[152:155], v[176:179], v[32:35]
	v_mfma_f32_16x16x32_bf16 v[132:135], v[144:147], v[196:199], v[132:135]
	v_mfma_f32_16x16x32_bf16 v[60:63], v[152:155], v[196:199], v[60:63]
	v_mfma_f32_16x16x32_bf16 v[128:131], v[148:151], v[164:167], v[128:131]
	v_mfma_f32_16x16x32_bf16 v[80:83], v[156:159], v[164:167], v[80:83]
	v_mfma_f32_16x16x32_bf16 v[112:115], v[148:151], v[172:175], v[112:115]
	v_mfma_f32_16x16x32_bf16 v[40:43], v[156:159], v[172:175], v[40:43]
	v_mfma_f32_16x16x32_bf16 v[104:107], v[148:151], v[180:183], v[104:107]
	v_mfma_f32_16x16x32_bf16 v[32:35], v[156:159], v[180:183], v[32:35]
	v_mfma_f32_16x16x32_bf16 v[132:135], v[148:151], v[200:203], v[132:135]
	v_mfma_f32_16x16x32_bf16 v[60:63], v[156:159], v[200:203], v[60:63]
	s_setprio 0
	s_barrier
	s_add_i32 s18, s23, s51
	v_lshl_add_u64 v[204:205], v[204:205], 0, s[58:59]
	s_mov_b32 m0, s18
	ds_read_b128 v[160:163], v236 offset:49152
	ds_read_b128 v[164:167], v236 offset:50176
	ds_read_b128 v[168:171], v236 offset:51200
	ds_read_b128 v[172:175], v236 offset:52224
	ds_read_b128 v[176:179], v236 offset:53248
	ds_read_b128 v[180:183], v236 offset:54272
	ds_read_b128 v[196:199], v236 offset:55296
	ds_read_b128 v[200:203], v236 offset:56320
	global_load_lds_dwordx4 v[204:205], off
	s_add_i32 m0, s18, 0x2000
	s_add_u32 s16, s16, 0x84080
	v_lshl_add_u64 v[204:205], v[206:207], 0, s[58:59]
	s_addc_u32 s17, s17, 0
	s_add_i32 s18, s24, s51
	global_load_lds_dwordx4 v[204:205], off
	v_lshl_add_u64 v[204:205], s[16:17], 0, v[188:189]
	s_mov_b32 m0, s18
	s_nop 0
	global_load_lds_dwordx4 v[204:205], off
	v_lshl_add_u64 v[204:205], s[16:17], 0, v[184:185]
	s_add_i32 m0, s18, 0x2000
	s_nop 0
	global_load_lds_dwordx4 v[204:205], off
	v_lshl_add_u64 v[204:205], v[208:209], 0, s[58:59]
	s_mov_b32 m0, s31
	s_nop 0
	global_load_lds_dwordx4 v[204:205], off
	v_lshl_add_u64 v[204:205], v[210:211], 0, s[58:59]
	s_mov_b32 m0, s38
	s_nop 0
	global_load_lds_dwordx4 v[204:205], off
	s_waitcnt vmcnt(8)
	s_waitcnt lgkmcnt(0)
	s_barrier
	s_setprio 1
	s_waitcnt lgkmcnt(0)
	v_mfma_f32_16x16x32_bf16 v[124:127], v[88:91], v[160:163], v[124:127]
	v_mfma_f32_16x16x32_bf16 v[52:55], v[100:103], v[160:163], v[52:55]
	v_mfma_f32_16x16x32_bf16 v[76:79], v[88:91], v[168:171], v[76:79]
	v_mfma_f32_16x16x32_bf16 v[12:15], v[100:103], v[168:171], v[12:15]
	v_mfma_f32_16x16x32_bf16 v[68:71], v[88:91], v[176:179], v[68:71]
	v_mfma_f32_16x16x32_bf16 v[4:7], v[100:103], v[176:179], v[4:7]
	v_mfma_f32_16x16x32_bf16 v[24:27], v[88:91], v[196:199], v[24:27]
	v_mfma_f32_16x16x32_bf16 v[16:19], v[100:103], v[196:199], v[16:19]
	v_mfma_f32_16x16x32_bf16 v[124:127], v[96:99], v[164:167], v[124:127]
	v_mfma_f32_16x16x32_bf16 v[52:55], v[120:123], v[164:167], v[52:55]
	v_mfma_f32_16x16x32_bf16 v[76:79], v[96:99], v[172:175], v[76:79]
	v_mfma_f32_16x16x32_bf16 v[12:15], v[120:123], v[172:175], v[12:15]
	v_mfma_f32_16x16x32_bf16 v[68:71], v[96:99], v[180:183], v[68:71]
	v_mfma_f32_16x16x32_bf16 v[4:7], v[120:123], v[180:183], v[4:7]
	v_mfma_f32_16x16x32_bf16 v[88:91], v[96:99], v[200:203], v[24:27]
	v_mfma_f32_16x16x32_bf16 v[16:19], v[120:123], v[200:203], v[16:19]
	v_mfma_f32_16x16x32_bf16 v[24:27], v[144:147], v[160:163], v[28:31]
	v_mfma_f32_16x16x32_bf16 v[120:123], v[148:151], v[164:167], v[24:27]
	v_mfma_f32_16x16x32_bf16 v[24:27], v[152:155], v[160:163], v[48:51]
	v_mfma_f32_16x16x32_bf16 v[48:51], v[156:159], v[164:167], v[24:27]
	v_mfma_f32_16x16x32_bf16 v[24:27], v[144:147], v[168:171], v[72:75]
	v_mfma_f32_16x16x32_bf16 v[72:75], v[148:151], v[172:175], v[24:27]
	v_mfma_f32_16x16x32_bf16 v[24:27], v[144:147], v[176:179], v[64:67]
	v_mfma_f32_16x16x32_bf16 v[8:11], v[152:155], v[168:171], v[8:11]
	v_mfma_f32_16x16x32_bf16 v[64:67], v[148:151], v[180:183], v[24:27]
	v_mfma_f32_16x16x32_bf16 v[0:3], v[152:155], v[176:179], v[0:3]
	v_mfma_f32_16x16x32_bf16 v[24:27], v[144:147], v[196:199], v[92:95]
	v_mfma_f32_16x16x32_bf16 v[20:23], v[152:155], v[196:199], v[20:23]
	v_mfma_f32_16x16x32_bf16 v[8:11], v[156:159], v[172:175], v[8:11]
	v_mfma_f32_16x16x32_bf16 v[0:3], v[156:159], v[180:183], v[0:3]
	v_mfma_f32_16x16x32_bf16 v[92:95], v[148:151], v[200:203], v[24:27]
	v_mfma_f32_16x16x32_bf16 v[20:23], v[156:159], v[200:203], v[20:23]
	s_setprio 0
	s_barrier
	s_add_i32 s22, s22, 2
	s_add_u32 s14, s14, 0x100
	s_addc_u32 s15, s15, 0
	s_add_u32 s20, s20, 0x100
	s_addc_u32 s21, s21, 0
	s_cmp_gt_u32 s22, 29
	s_cbranch_scc0 .LBB0_1391
	s_and_b64 vcc, exec, s[82:83]
	s_cbranch_vccz .LBB0_1394
	s_barrier

.LBB0_1626:
	ds_read_b128 v[128:131], v224
	ds_read_b128 v[132:135], v224 offset:1024
	ds_read_b128 v[136:139], v224 offset:2048
	ds_read_b128 v[140:143], v224 offset:3072
	ds_read_b128 v[154:157], v225
	ds_read_b128 v[158:161], v225 offset:1024
	ds_read_b128 v[162:165], v225 offset:2048
	ds_read_b128 v[166:169], v225 offset:3072
	s_add_i32 s48, s34, 2
	s_add_u32 s35, s26, 0xffea0080
	s_addc_u32 s49, s27, -1
	s_cmp_eq_u32 s30, s34
	s_cselect_b32 s34, s54, s31
	s_cselect_b32 s61, s53, s49
	s_cselect_b32 s60, s52, s35
	s_cselect_b32 s35, s55, s33
	v_lshl_add_u64 v[202:203], s[26:27], 0, v[150:151]
	s_add_i32 m0, s66, 0xc000
	ds_read_b128 v[170:173], v226
	ds_read_b128 v[174:177], v226 offset:1024
	ds_read_b128 v[178:181], v226 offset:2048
	ds_read_b128 v[182:185], v226 offset:3072
	ds_read_b128 v[186:189], v226 offset:4096
	ds_read_b128 v[190:193], v226 offset:5120
	ds_read_b128 v[194:197], v226 offset:6144
	ds_read_b128 v[198:201], v226 offset:7168
	global_load_lds_dwordx4 v[202:203], off
	v_lshl_add_u64 v[202:203], s[26:27], 0, v[152:153]
	s_add_i32 m0, s66, 0xe000
	s_nop 0
	global_load_lds_dwordx4 v[202:203], off
	s_waitcnt vmcnt(8)
	s_waitcnt lgkmcnt(0)
	s_barrier
	s_setprio 1
	s_waitcnt lgkmcnt(0)
	v_mfma_f32_16x16x32_bf16 v[124:127], v[128:131], v[170:173], v[124:127]
	v_mfma_f32_16x16x32_bf16 v[120:123], v[136:139], v[170:173], v[120:123]
	v_mfma_f32_16x16x32_bf16 v[112:115], v[128:131], v[178:181], v[112:115]
	v_mfma_f32_16x16x32_bf16 v[104:107], v[136:139], v[178:181], v[104:107]
	v_mfma_f32_16x16x32_bf16 v[96:99], v[128:131], v[186:189], v[96:99]
	v_mfma_f32_16x16x32_bf16 v[88:91], v[136:139], v[186:189], v[88:91]
	v_mfma_f32_16x16x32_bf16 v[80:83], v[128:131], v[194:197], v[80:83]
	v_mfma_f32_16x16x32_bf16 v[72:75], v[136:139], v[194:197], v[72:75]
	v_mfma_f32_16x16x32_bf16 v[124:127], v[132:135], v[174:177], v[124:127]
	v_mfma_f32_16x16x32_bf16 v[120:123], v[140:143], v[174:177], v[120:123]
	v_mfma_f32_16x16x32_bf16 v[112:115], v[132:135], v[182:185], v[112:115]
	v_mfma_f32_16x16x32_bf16 v[104:107], v[140:143], v[182:185], v[104:107]
	v_mfma_f32_16x16x32_bf16 v[96:99], v[132:135], v[190:193], v[96:99]
	v_mfma_f32_16x16x32_bf16 v[88:91], v[140:143], v[190:193], v[88:91]
	v_mfma_f32_16x16x32_bf16 v[80:83], v[132:135], v[198:201], v[80:83]
	v_mfma_f32_16x16x32_bf16 v[72:75], v[140:143], v[198:201], v[72:75]
	v_mfma_f32_16x16x32_bf16 v[116:119], v[154:157], v[170:173], v[116:119]
	v_mfma_f32_16x16x32_bf16 v[108:111], v[162:165], v[170:173], v[108:111]
	v_mfma_f32_16x16x32_bf16 v[100:103], v[154:157], v[178:181], v[100:103]
	v_mfma_f32_16x16x32_bf16 v[92:95], v[162:165], v[178:181], v[92:95]
	v_mfma_f32_16x16x32_bf16 v[84:87], v[154:157], v[186:189], v[84:87]
	v_mfma_f32_16x16x32_bf16 v[76:79], v[162:165], v[186:189], v[76:79]
	v_mfma_f32_16x16x32_bf16 v[68:71], v[154:157], v[194:197], v[68:71]
	v_mfma_f32_16x16x32_bf16 v[64:67], v[162:165], v[194:197], v[64:67]
	v_mfma_f32_16x16x32_bf16 v[116:119], v[158:161], v[174:177], v[116:119]
	v_mfma_f32_16x16x32_bf16 v[108:111], v[166:169], v[174:177], v[108:111]
	v_mfma_f32_16x16x32_bf16 v[100:103], v[158:161], v[182:185], v[100:103]
	v_mfma_f32_16x16x32_bf16 v[92:95], v[166:169], v[182:185], v[92:95]
	v_mfma_f32_16x16x32_bf16 v[84:87], v[158:161], v[190:193], v[84:87]
	v_mfma_f32_16x16x32_bf16 v[76:79], v[166:169], v[190:193], v[76:79]
	v_mfma_f32_16x16x32_bf16 v[68:71], v[158:161], v[198:201], v[68:71]
	v_mfma_f32_16x16x32_bf16 v[64:67], v[166:169], v[198:201], v[64:67]
	s_setprio 0
	s_barrier
	s_add_i32 s49, s79, s65
	v_lshl_add_u64 v[202:203], s[34:35], 0, v[144:145]
	s_mov_b32 m0, s49
	ds_read_b128 v[170:173], v226 offset:16384
	ds_read_b128 v[174:177], v226 offset:17408
	ds_read_b128 v[178:181], v226 offset:18432
	ds_read_b128 v[182:185], v226 offset:19456
	ds_read_b128 v[186:189], v226 offset:20480
	ds_read_b128 v[190:193], v226 offset:21504
	ds_read_b128 v[194:197], v226 offset:22528
	ds_read_b128 v[198:201], v226 offset:23552
	global_load_lds_dwordx4 v[202:203], off
	s_add_i32 m0, s49, 0x2000
	s_add_u32 s50, s34, 0x160000
	v_lshl_add_u64 v[204:205], s[34:35], 0, v[146:147]
	s_addc_u32 s51, s35, 0
	s_add_i32 s49, s84, s65
	global_load_lds_dwordx4 v[204:205], off
	v_lshl_add_u64 v[206:207], s[50:51], 0, v[144:145]
	s_mov_b32 m0, s49
	v_lshl_add_u64 v[208:209], s[60:61], 0, v[146:147]
	global_load_lds_dwordx4 v[206:207], off
	v_lshl_add_u64 v[206:207], s[50:51], 0, v[146:147]
	s_add_i32 m0, s49, 0x2000
	s_nop 0
	global_load_lds_dwordx4 v[206:207], off
	v_lshl_add_u64 v[206:207], s[60:61], 0, v[144:145]
	s_mov_b32 m0, s66
	s_nop 0
	global_load_lds_dwordx4 v[206:207], off
	s_mov_b32 m0, s67
	s_nop 0
	global_load_lds_dwordx4 v[208:209], off
	s_waitcnt vmcnt(8)
	s_waitcnt lgkmcnt(0)
	s_barrier
	s_setprio 1
	s_waitcnt lgkmcnt(0)
	v_mfma_f32_16x16x32_bf16 v[60:63], v[128:131], v[170:173], v[60:63]
	v_mfma_f32_16x16x32_bf16 v[56:59], v[136:139], v[170:173], v[56:59]
	v_mfma_f32_16x16x32_bf16 v[48:51], v[128:131], v[178:181], v[48:51]
	v_mfma_f32_16x16x32_bf16 v[40:43], v[136:139], v[178:181], v[40:43]
	v_mfma_f32_16x16x32_bf16 v[32:35], v[128:131], v[186:189], v[32:35]
	v_mfma_f32_16x16x32_bf16 v[24:27], v[136:139], v[186:189], v[24:27]
	v_mfma_f32_16x16x32_bf16 v[16:19], v[128:131], v[194:197], v[16:19]
	v_mfma_f32_16x16x32_bf16 v[8:11], v[136:139], v[194:197], v[8:11]
	v_mfma_f32_16x16x32_bf16 v[60:63], v[132:135], v[174:177], v[60:63]
	v_mfma_f32_16x16x32_bf16 v[56:59], v[140:143], v[174:177], v[56:59]
	v_mfma_f32_16x16x32_bf16 v[48:51], v[132:135], v[182:185], v[48:51]
	v_mfma_f32_16x16x32_bf16 v[40:43], v[140:143], v[182:185], v[40:43]
	v_mfma_f32_16x16x32_bf16 v[32:35], v[132:135], v[190:193], v[32:35]
	v_mfma_f32_16x16x32_bf16 v[24:27], v[140:143], v[190:193], v[24:27]
	v_mfma_f32_16x16x32_bf16 v[16:19], v[132:135], v[198:201], v[16:19]
	v_mfma_f32_16x16x32_bf16 v[8:11], v[140:143], v[198:201], v[8:11]
	v_mfma_f32_16x16x32_bf16 v[52:55], v[154:157], v[170:173], v[52:55]
	v_mfma_f32_16x16x32_bf16 v[44:47], v[162:165], v[170:173], v[44:47]
	v_mfma_f32_16x16x32_bf16 v[36:39], v[154:157], v[178:181], v[36:39]
	v_mfma_f32_16x16x32_bf16 v[28:31], v[162:165], v[178:181], v[28:31]
	v_mfma_f32_16x16x32_bf16 v[20:23], v[154:157], v[186:189], v[20:23]
	v_mfma_f32_16x16x32_bf16 v[12:15], v[162:165], v[186:189], v[12:15]
	v_mfma_f32_16x16x32_bf16 v[4:7], v[154:157], v[194:197], v[4:7]
	v_mfma_f32_16x16x32_bf16 v[0:3], v[162:165], v[194:197], v[0:3]
	v_mfma_f32_16x16x32_bf16 v[52:55], v[158:161], v[174:177], v[52:55]
	v_mfma_f32_16x16x32_bf16 v[44:47], v[166:169], v[174:177], v[44:47]
	v_mfma_f32_16x16x32_bf16 v[36:39], v[158:161], v[182:185], v[36:39]
	v_mfma_f32_16x16x32_bf16 v[28:31], v[166:169], v[182:185], v[28:31]
	v_mfma_f32_16x16x32_bf16 v[20:23], v[158:161], v[190:193], v[20:23]
	v_mfma_f32_16x16x32_bf16 v[12:15], v[166:169], v[190:193], v[12:15]
	v_mfma_f32_16x16x32_bf16 v[4:7], v[158:161], v[198:201], v[4:7]
	v_mfma_f32_16x16x32_bf16 v[0:3], v[166:169], v[198:201], v[0:3]
	s_setprio 0
	s_barrier
	s_add_i32 s49, 0, 0x18000
	s_add_i32 s57, 0, 0x1c000
	v_add_u32_e32 v140, s49, v220
	v_add_u32_e32 v166, s57, v220
	ds_read_b128 v[128:131], v140
	ds_read_b128 v[132:135], v140 offset:1024
	ds_read_b128 v[136:139], v140 offset:2048
	ds_read_b128 v[140:143], v140 offset:3072
	ds_read_b128 v[154:157], v166
	ds_read_b128 v[158:161], v166 offset:1024
	ds_read_b128 v[162:165], v166 offset:2048
	ds_read_b128 v[166:169], v166 offset:3072
	s_add_u32 s50, s60, 0x160000
	s_addc_u32 s51, s61, 0
	s_mov_b32 m0, s68
	v_lshl_add_u64 v[210:211], s[50:51], 0, v[144:145]
	ds_read_b128 v[170:173], v226 offset:32768
	ds_read_b128 v[174:177], v226 offset:33792
	ds_read_b128 v[178:181], v226 offset:34816
	ds_read_b128 v[182:185], v226 offset:35840
	ds_read_b128 v[186:189], v226 offset:36864
	ds_read_b128 v[190:193], v226 offset:37888
	ds_read_b128 v[194:197], v226 offset:38912
	ds_read_b128 v[198:201], v226 offset:39936
	global_load_lds_dwordx4 v[210:211], off
	v_lshl_add_u64 v[210:211], s[50:51], 0, v[146:147]
	s_mov_b32 m0, s69
	s_nop 0
	global_load_lds_dwordx4 v[210:211], off
	s_waitcnt vmcnt(8)
	s_waitcnt lgkmcnt(0)
	s_barrier
	s_setprio 1
	s_waitcnt lgkmcnt(0)
	v_mfma_f32_16x16x32_bf16 v[124:127], v[128:131], v[170:173], v[124:127]
	v_mfma_f32_16x16x32_bf16 v[120:123], v[136:139], v[170:173], v[120:123]
	v_mfma_f32_16x16x32_bf16 v[112:115], v[128:131], v[178:181], v[112:115]
	v_mfma_f32_16x16x32_bf16 v[104:107], v[136:139], v[178:181], v[104:107]
	v_mfma_f32_16x16x32_bf16 v[96:99], v[128:131], v[186:189], v[96:99]
	v_mfma_f32_16x16x32_bf16 v[88:91], v[136:139], v[186:189], v[88:91]
	v_mfma_f32_16x16x32_bf16 v[80:83], v[128:131], v[194:197], v[80:83]
	v_mfma_f32_16x16x32_bf16 v[72:75], v[136:139], v[194:197], v[72:75]
	v_mfma_f32_16x16x32_bf16 v[124:127], v[132:135], v[174:177], v[124:127]
	v_mfma_f32_16x16x32_bf16 v[120:123], v[140:143], v[174:177], v[120:123]
	v_mfma_f32_16x16x32_bf16 v[112:115], v[132:135], v[182:185], v[112:115]
	v_mfma_f32_16x16x32_bf16 v[104:107], v[140:143], v[182:185], v[104:107]
	v_mfma_f32_16x16x32_bf16 v[96:99], v[132:135], v[190:193], v[96:99]
	v_mfma_f32_16x16x32_bf16 v[88:91], v[140:143], v[190:193], v[88:91]
	v_mfma_f32_16x16x32_bf16 v[80:83], v[132:135], v[198:201], v[80:83]
	v_mfma_f32_16x16x32_bf16 v[72:75], v[140:143], v[198:201], v[72:75]
	v_mfma_f32_16x16x32_bf16 v[116:119], v[154:157], v[170:173], v[116:119]
	v_mfma_f32_16x16x32_bf16 v[108:111], v[162:165], v[170:173], v[108:111]
	v_mfma_f32_16x16x32_bf16 v[100:103], v[154:157], v[178:181], v[100:103]
	v_mfma_f32_16x16x32_bf16 v[92:95], v[162:165], v[178:181], v[92:95]
	v_mfma_f32_16x16x32_bf16 v[84:87], v[154:157], v[186:189], v[84:87]
	v_mfma_f32_16x16x32_bf16 v[76:79], v[162:165], v[186:189], v[76:79]
	v_mfma_f32_16x16x32_bf16 v[68:71], v[154:157], v[194:197], v[68:71]
	v_mfma_f32_16x16x32_bf16 v[64:67], v[162:165], v[194:197], v[64:67]
	v_mfma_f32_16x16x32_bf16 v[116:119], v[158:161], v[174:177], v[116:119]
	v_mfma_f32_16x16x32_bf16 v[108:111], v[166:169], v[174:177], v[108:111]
	v_mfma_f32_16x16x32_bf16 v[100:103], v[158:161], v[182:185], v[100:103]
	v_mfma_f32_16x16x32_bf16 v[92:95], v[166:169], v[182:185], v[92:95]
	v_mfma_f32_16x16x32_bf16 v[84:87], v[158:161], v[190:193], v[84:87]
	v_mfma_f32_16x16x32_bf16 v[76:79], v[166:169], v[190:193], v[76:79]
	v_mfma_f32_16x16x32_bf16 v[68:71], v[158:161], v[198:201], v[68:71]
	v_mfma_f32_16x16x32_bf16 v[64:67], v[166:169], v[198:201], v[64:67]
	s_setprio 0
	s_barrier
	s_add_i32 s49, s49, s65
	v_lshl_add_u64 v[202:203], v[202:203], 0, s[24:25]
	s_mov_b32 m0, s49
	ds_read_b128 v[170:173], v226 offset:49152
	ds_read_b128 v[174:177], v226 offset:50176
	ds_read_b128 v[178:181], v226 offset:51200
	ds_read_b128 v[182:185], v226 offset:52224
	ds_read_b128 v[186:189], v226 offset:53248
	ds_read_b128 v[190:193], v226 offset:54272
	ds_read_b128 v[194:197], v226 offset:55296
	ds_read_b128 v[198:201], v226 offset:56320
	global_load_lds_dwordx4 v[202:203], off
	s_add_i32 m0, s49, 0x2000
	s_add_u32 s34, s34, 0x160080
	v_lshl_add_u64 v[202:203], v[204:205], 0, s[24:25]
	s_addc_u32 s35, s35, 0
	s_add_i32 s49, s57, s65
	global_load_lds_dwordx4 v[202:203], off
	v_lshl_add_u64 v[202:203], s[34:35], 0, v[144:145]
	s_mov_b32 m0, s49
	s_nop 0
	global_load_lds_dwordx4 v[202:203], off
	v_lshl_add_u64 v[202:203], s[34:35], 0, v[146:147]
	s_add_i32 m0, s49, 0x2000
	s_nop 0
	global_load_lds_dwordx4 v[202:203], off
	v_lshl_add_u64 v[202:203], v[206:207], 0, s[24:25]
	s_mov_b32 m0, s74
	s_nop 0
	global_load_lds_dwordx4 v[202:203], off
	v_lshl_add_u64 v[202:203], v[208:209], 0, s[24:25]
	s_mov_b32 m0, s75
	s_nop 0
	global_load_lds_dwordx4 v[202:203], off
	s_waitcnt vmcnt(8)
	s_waitcnt lgkmcnt(0)
	s_barrier
	s_setprio 1
	s_waitcnt lgkmcnt(0)
	v_mfma_f32_16x16x32_bf16 v[60:63], v[128:131], v[170:173], v[60:63]
	v_mfma_f32_16x16x32_bf16 v[56:59], v[136:139], v[170:173], v[56:59]
	v_mfma_f32_16x16x32_bf16 v[48:51], v[128:131], v[178:181], v[48:51]
	v_mfma_f32_16x16x32_bf16 v[40:43], v[136:139], v[178:181], v[40:43]
	v_mfma_f32_16x16x32_bf16 v[32:35], v[128:131], v[186:189], v[32:35]
	v_mfma_f32_16x16x32_bf16 v[24:27], v[136:139], v[186:189], v[24:27]
	v_mfma_f32_16x16x32_bf16 v[16:19], v[128:131], v[194:197], v[16:19]
	v_mfma_f32_16x16x32_bf16 v[8:11], v[136:139], v[194:197], v[8:11]
	v_mfma_f32_16x16x32_bf16 v[60:63], v[132:135], v[174:177], v[60:63]
	v_mfma_f32_16x16x32_bf16 v[56:59], v[140:143], v[174:177], v[56:59]
	v_mfma_f32_16x16x32_bf16 v[48:51], v[132:135], v[182:185], v[48:51]
	v_mfma_f32_16x16x32_bf16 v[40:43], v[140:143], v[182:185], v[40:43]
	v_mfma_f32_16x16x32_bf16 v[32:35], v[132:135], v[190:193], v[32:35]
	v_mfma_f32_16x16x32_bf16 v[24:27], v[140:143], v[190:193], v[24:27]
	v_mfma_f32_16x16x32_bf16 v[16:19], v[132:135], v[198:201], v[16:19]
	v_mfma_f32_16x16x32_bf16 v[8:11], v[140:143], v[198:201], v[8:11]
	v_mfma_f32_16x16x32_bf16 v[52:55], v[154:157], v[170:173], v[52:55]
	v_mfma_f32_16x16x32_bf16 v[44:47], v[162:165], v[170:173], v[44:47]
	v_mfma_f32_16x16x32_bf16 v[36:39], v[154:157], v[178:181], v[36:39]
	v_mfma_f32_16x16x32_bf16 v[28:31], v[162:165], v[178:181], v[28:31]
	v_mfma_f32_16x16x32_bf16 v[20:23], v[154:157], v[186:189], v[20:23]
	v_mfma_f32_16x16x32_bf16 v[12:15], v[162:165], v[186:189], v[12:15]
	v_mfma_f32_16x16x32_bf16 v[4:7], v[154:157], v[194:197], v[4:7]
	v_mfma_f32_16x16x32_bf16 v[0:3], v[162:165], v[194:197], v[0:3]
	v_mfma_f32_16x16x32_bf16 v[52:55], v[158:161], v[174:177], v[52:55]
	v_mfma_f32_16x16x32_bf16 v[44:47], v[166:169], v[174:177], v[44:47]
	v_mfma_f32_16x16x32_bf16 v[36:39], v[158:161], v[182:185], v[36:39]
	v_mfma_f32_16x16x32_bf16 v[28:31], v[166:169], v[182:185], v[28:31]
	v_mfma_f32_16x16x32_bf16 v[20:23], v[158:161], v[190:193], v[20:23]
	v_mfma_f32_16x16x32_bf16 v[12:15], v[166:169], v[190:193], v[12:15]
	v_mfma_f32_16x16x32_bf16 v[4:7], v[158:161], v[198:201], v[4:7]
	v_mfma_f32_16x16x32_bf16 v[0:3], v[166:169], v[198:201], v[0:3]
	s_setprio 0
	s_barrier
	s_add_u32 s26, s26, 0x100
	s_addc_u32 s27, s27, 0
	s_add_u32 s31, s31, 0x100
	s_addc_u32 s33, s33, 0
	s_cmp_ge_u32 s48, s16
	s_mov_b32 s34, s48
	s_cbranch_scc0 .LBB0_1626
	s_and_b64 vcc, exec, s[28:29]
	s_cbranch_vccz .LBB0_1629
	s_barrier
